# adds G3 conv-coefficient prefetch one column ahead and scalar ssq sums on top of the legacy-mul fusion
# speedup vs baseline: 1.0134x; 1.0026x over previous
; __device__ __forceinline__ float bperm_f(int src_lane, float v) { return __builtin_bit_cast(float, __builtin_amdgcn_ds_bpermute(src_lane << 2, __builtin_bit_cast(int, v))); }
;     __device__ __forceinline__ void operator()(Acc& acc, const Unit& u, int wr, int wc, int fr, int fq) const {
;         const int b = u.pm / UPU, j = u.pm % UPU;
;         const int tbase = 252 * j + 126 * wr - 2 + fr;
;         const int ch0 = 128 * u.pn + 32 * wc + 8 * fq;
;         float chain = 0.f;
;         { const int ln = (fq << 4) | fr; f32x4 pq[8];
; #pragma unroll
;           for (int q = 0; q < 8; ++q) { const int t = tbase + 16 * q; const bool ok = (t >= 0) && (t < SEQ); pq[q] = *(const f32x4*)(ssq + (size_t)(b * SEQ + (ok ? t : 0)) * 16 + 4 * fq); }
; #pragma unroll
;           for (int q = 0; q < 8; ++q) {
;             const int t = tbase + 16 * q; const bool ok = (t >= 0) && (t < SEQ);
;             float sq = (pq[q][0] + pq[q][1]) + (pq[q][2] + pq[q][3]); sq += bperm_f(ln ^ 16, sq); sq += bperm_f(ln ^ 32, sq);
;             const float rs = rsqrtf(sq * (1.0f / DM) + EPS);
.LBB0_43:
	s_mul_hi_i32 s21, s20, 0x3e0f83e1
	s_lshr_b32 s27, s21, 31
	s_ashr_i32 s21, s21, 3
	s_add_i32 s21, s21, s27
	s_mul_i32 s27, s21, 33
	s_sub_i32 s20, s20, s27
	s_mulk_i32 s20, 0xfc
	v_add_u32_e32 v198, s20, v194
	v_add_u32_e32 v223, 16, v198
	v_cmp_gt_u32_e64 s[56:57], s97, v198
	v_cmp_gt_u32_e64 s[52:53], s97, v223
	s_lshl_b32 s20, s21, 13
	v_cndmask_b32_e64 v132, 0, v198, s[56:57]
	v_cndmask_b32_e64 v136, 0, v223, s[52:53]
	v_add_u32_e32 v132, s20, v132
	v_add_u32_e32 v136, s20, v136
	v_ashrrev_i32_e32 v133, 31, v132
	v_ashrrev_i32_e32 v137, 31, v136
	v_lshlrev_b64 v[132:133], 6, v[132:133]
	v_lshlrev_b64 v[136:137], 6, v[136:137]
	v_lshl_add_u64 v[132:133], v[146:147], 0, v[132:133]
	v_lshl_add_u64 v[136:137], v[146:147], 0, v[136:137]
	flat_load_dwordx4 v[132:135], v[132:133]
	v_add_u32_e32 v227, 32, v198
	flat_load_dwordx4 v[136:139], v[136:137]
	v_add_u32_e32 v226, 48, v198
	v_cmp_gt_u32_e64 s[54:55], s97, v227
	v_add_u32_e32 v225, 64, v198
	v_cmp_gt_u32_e64 s[50:51], s97, v226
	v_cndmask_b32_e64 v152, 0, v227, s[54:55]
	v_cmp_gt_u32_e64 s[48:49], s97, v225
	v_cndmask_b32_e64 v153, 0, v226, s[50:51]
	v_add_u32_e32 v152, s20, v152
	v_cndmask_b32_e64 v155, 0, v225, s[48:49]
	v_add_u32_e32 v154, s20, v153
	v_ashrrev_i32_e32 v153, 31, v152
	v_add_u32_e32 v156, s20, v155
	v_ashrrev_i32_e32 v155, 31, v154
	v_lshlrev_b64 v[152:153], 6, v[152:153]
	v_lshlrev_b64 v[154:155], 6, v[154:155]
	v_add_u32_e32 v224, 0x50, v198
	v_cmp_gt_u32_e64 s[46:47], s97, v224
	s_mov_b32 s44, 0x358637bd
	v_add_u32_e32 v222, 0x60, v198
	v_add_u32_e32 v199, 0x70, v198
	v_cndmask_b32_e64 v157, 0, v224, s[46:47]
	v_mov_b64_e32 v[188:189], s[44:45]
	v_cmp_gt_u32_e64 s[44:45], s97, v222
	v_cmp_gt_u32_e32 vcc, s97, v199
	v_add_u32_e32 v158, s20, v157
	v_ashrrev_i32_e32 v157, 31, v156
	v_cndmask_b32_e64 v159, 0, v222, s[44:45]
	v_cndmask_b32_e32 v161, 0, v199, vcc
	v_lshlrev_b64 v[156:157], 6, v[156:157]
	s_mov_b32 s90, 0x3a800000
	v_add_u32_e32 v160, s20, v159
	v_add_u32_e32 v162, s20, v161
	v_ashrrev_i32_e32 v159, 31, v158
	v_ashrrev_i32_e32 v161, 31, v160
	v_ashrrev_i32_e32 v163, 31, v162
	v_lshlrev_b64 v[158:159], 6, v[158:159]
	v_lshlrev_b64 v[160:161], 6, v[160:161]
	v_lshlrev_b64 v[162:163], 6, v[162:163]
	s_waitcnt vmcnt(0) lgkmcnt(0)
	v_add_f32_e32 v174, v133, v132
	v_add_f32_e32 v175, v134, v135
	v_add_f32_e32 v133, v174, v175
	v_add_f32_e32 v174, v137, v136
	v_add_f32_e32 v175, v138, v139
	v_add_f32_e32 v132, v174, v175
	v_lshl_add_u64 v[136:137], v[146:147], 0, v[152:153]
	v_lshl_add_u64 v[138:139], v[146:147], 0, v[154:155]
	flat_load_dwordx4 v[190:193], v[136:137]
	flat_load_dwordx4 v[228:231], v[138:139]
	ds_bpermute_b32 v135, v195, v133
	ds_bpermute_b32 v134, v195, v132
	v_lshl_add_u64 v[136:137], v[146:147], 0, v[156:157]
	v_lshl_add_u64 v[138:139], v[146:147], 0, v[158:159]
	v_lshl_add_u64 v[152:153], v[146:147], 0, v[160:161]
	v_lshl_add_u64 v[154:155], v[146:147], 0, v[162:163]
	s_waitcnt lgkmcnt(0)
	v_pk_add_f32 v[132:133], v[132:133], v[134:135]
	ds_bpermute_b32 v135, v196, v133
	ds_bpermute_b32 v134, v196, v132
	s_waitcnt lgkmcnt(0)
	v_pk_add_f32 v[132:133], v[132:133], v[134:135]
	s_nop 0
	v_pk_fma_f32 v[156:157], v[132:133], s[90:91], v[188:189] op_sel_hi:[1,0,0]
	s_nop 0
	v_mul_f32_e32 v132, 0x4b800000, v157
	v_cmp_gt_f32_e64 s[58:59], s29, v157
	s_nop 1
	v_cndmask_b32_e64 v132, v157, v132, s[58:59]
	v_rsq_f32_e32 v157, v132
	flat_load_dwordx4 v[232:235], v[136:137]
	flat_load_dwordx4 v[236:239], v[138:139]
	s_nop 0
	flat_load_dwordx4 v[136:139], v[152:153]
	flat_load_dwordx4 v[132:135], v[154:155]
	v_mul_f32_e32 v152, 0x45800000, v157
	v_cndmask_b32_e64 v153, v157, v152, s[58:59]
	v_mul_f32_e32 v157, v122, v153
	v_cndmask_b32_e64 v153, 0, v153, s[56:57]
	v_mul_legacy_f32 v122, v126, v153
	v_mul_legacy_f32 v152, v108, v153
	v_mul_f32_e32 v108, v109, v153
	v_mul_f32_e32 v109, 0x4b800000, v156
	v_cmp_gt_f32_e64 s[58:59], s29, v156
	v_cndmask_b32_e64 v109, v156, v109, s[58:59]
	v_rsq_f32_e32 v109, v109
	v_mul_legacy_f32 v182, v128, v153
	v_cndmask_b32_e64 v128, 0, v108, s[56:57]
	v_mul_legacy_f32 v160, v130, v153
	v_mul_legacy_f32 v130, v124, v153
	v_mul_legacy_f32 v124, v110, v153
	v_mul_legacy_f32 v110, v111, v153
	v_mul_f32_e32 v108, 0x45800000, v109
	v_cndmask_b32_e64 v108, v109, v108, s[58:59]
	v_cndmask_b32_e64 v108, 0, v108, s[52:53]
	v_mul_legacy_f32 v187, v116, v108
	v_mul_legacy_f32 v181, v117, v108
	v_mul_legacy_f32 v175, v118, v108
	v_cndmask_b32_e64 v162, 0, v157, s[56:57]
	v_mul_legacy_f32 v157, v119, v108
	v_mul_legacy_f32 v119, v112, v108
	v_mul_legacy_f32 v117, v113, v108
	v_mul_legacy_f32 v186, v104, v108
	v_mul_legacy_f32 v113, v114, v108
	v_mul_f32_e32 v109, v115, v108
	v_mul_legacy_f32 v180, v105, v108
	v_mul_legacy_f32 v174, v106, v108
	v_mul_legacy_f32 v156, v107, v108
	v_mul_legacy_f32 v118, v92, v108
	s_waitcnt vmcnt(0)
	v_add_f32_e32 v114, v191, v190
	v_add_f32_e32 v115, v192, v193
	v_add_f32_e32 v105, v114, v115
	v_add_f32_e32 v114, v229, v228
	v_add_f32_e32 v115, v230, v231
	v_add_f32_e32 v104, v114, v115
	ds_bpermute_b32 v115, v195, v105
	ds_bpermute_b32 v114, v195, v104
	v_mul_legacy_f32 v116, v93, v108
	s_waitcnt lgkmcnt(0)
	v_pk_add_f32 v[104:105], v[104:105], v[114:115]
	ds_bpermute_b32 v107, v196, v105
	ds_bpermute_b32 v106, v196, v104
	v_mul_f32_e32 v155, v120, v153
	v_mul_legacy_f32 v178, v121, v153
	s_waitcnt lgkmcnt(0)
; __device__ __forceinline__ float bperm_f(int src_lane, float v) { return __builtin_bit_cast(float, __builtin_amdgcn_ds_bpermute(src_lane << 2, __builtin_bit_cast(int, v))); }
;     __device__ __forceinline__ void operator()(Acc& acc, const Unit& u, int wr, int wc, int fr, int fq) const {
;     ...
;           for (int q = 0; q < 8; ++q) {
;             const int t = tbase + 16 * q; const bool ok = (t >= 0) && (t < SEQ);
;             float sq = (pq[q][0] + pq[q][1]) + (pq[q][2] + pq[q][3]); sq += bperm_f(ln ^ 16, sq); sq += bperm_f(ln ^ 32, sq);
;             const float rs = rsqrtf(sq * (1.0f / DM) + EPS);
; #pragma unroll
;             for (int bj = 0; bj < 2; ++bj)
; #pragma unroll
;                 for (int n = 0; n < 2; ++n)
; #pragma unroll
;                     for (int i = 0; i < 4; ++i) { const float v = acc[q >> 2][bj][q & 3][n][i]; acc[q >> 2][bj][q & 3][n][i] = ok ? v * rs : 0.f; }
;           }
	v_pk_add_f32 v[92:93], v[104:105], v[106:107]
	v_mul_legacy_f32 v176, v129, v153
	v_pk_fma_f32 v[92:93], v[92:93], s[90:91], v[188:189] op_sel_hi:[1,0,0]
	v_mul_legacy_f32 v154, v131, v153
	v_mul_legacy_f32 v126, v125, v153
	v_mul_legacy_f32 v120, v127, v153
	v_cndmask_b32_e64 v184, 0, v155, s[56:57]
	v_mul_legacy_f32 v158, v123, v153
	v_mul_f32_e32 v104, 0x4b800000, v93
	v_cmp_gt_f32_e64 s[56:57], s29, v93
	v_mul_legacy_f32 v112, v94, v108
	v_cndmask_b32_e64 v93, v93, v104, s[56:57]
	v_rsq_f32_e32 v93, v93
	v_mul_legacy_f32 v108, v95, v108
	v_cndmask_b32_e64 v109, 0, v109, s[52:53]
	v_mul_f32_e32 v94, 0x45800000, v93
	v_cndmask_b32_e64 v111, v93, v94, s[56:57]
	v_mul_f32_e32 v93, v100, v111
	v_cndmask_b32_e64 v111, 0, v111, s[54:55]
	v_mul_legacy_f32 v100, v76, v111
	v_mul_f32_e32 v76, v77, v111
	v_mul_f32_e32 v77, 0x4b800000, v92
	v_cmp_gt_f32_e64 s[52:53], s29, v92
	v_cndmask_b32_e64 v115, 0, v93, s[54:55]
	v_cndmask_b32_e64 v77, v92, v77, s[52:53]
	v_mul_legacy_f32 v107, v101, v111
	v_rsq_f32_e32 v77, v77
	v_mul_legacy_f32 v105, v102, v111
	v_mul_legacy_f32 v103, v103, v111
	v_mul_f32_e32 v93, v96, v111
	v_cndmask_b32_e64 v96, 0, v76, s[54:55]
	v_mul_legacy_f32 v94, v78, v111
	v_mul_legacy_f32 v92, v79, v111
	v_mul_f32_e32 v76, 0x45800000, v77
	v_cndmask_b32_e64 v101, 0, v93, s[54:55]
	v_cndmask_b32_e64 v76, v77, v76, s[52:53]
	v_mul_legacy_f32 v97, v97, v111
	v_mul_legacy_f32 v114, v88, v111
	v_mul_legacy_f32 v95, v98, v111
	v_mul_f32_e32 v93, v99, v111
	v_mul_legacy_f32 v106, v89, v111
	v_cndmask_b32_e64 v76, 0, v76, s[50:51]
	v_mul_legacy_f32 v99, v84, v76
	v_mul_legacy_f32 v104, v90, v111
	v_mul_f32_e32 v88, v91, v111
	v_mul_legacy_f32 v91, v85, v76
	v_mul_legacy_f32 v89, v86, v76
	v_mul_legacy_f32 v87, v87, v76
	v_mul_legacy_f32 v85, v80, v76
	v_mul_legacy_f32 v81, v81, v76
	v_mul_legacy_f32 v98, v72, v76
	v_mul_legacy_f32 v79, v82, v76
	v_mul_f32_e32 v77, v83, v76
	v_mul_legacy_f32 v90, v73, v76
	v_add_f32_e32 v82, v233, v232
	v_add_f32_e32 v83, v234, v235
	v_add_f32_e32 v73, v82, v83
	v_add_f32_e32 v82, v237, v236
	v_add_f32_e32 v83, v238, v239
	v_add_f32_e32 v72, v82, v83
	ds_bpermute_b32 v83, v195, v73
	ds_bpermute_b32 v82, v195, v72
	v_cndmask_b32_e64 v102, 0, v88, s[54:55]
	v_mul_legacy_f32 v88, v74, v76
	s_waitcnt lgkmcnt(0)
	v_pk_add_f32 v[72:73], v[72:73], v[82:83]
	v_mul_legacy_f32 v86, v75, v76
	ds_bpermute_b32 v75, v196, v73
	ds_bpermute_b32 v74, v196, v72
	v_mul_legacy_f32 v84, v68, v76
	v_mul_legacy_f32 v80, v69, v76
	s_waitcnt lgkmcnt(0)
	v_pk_add_f32 v[68:69], v[72:73], v[74:75]
	v_mul_f32_e32 v70, v70, v76
	v_pk_fma_f32 v[82:83], v[68:69], s[90:91], v[188:189] op_sel_hi:[1,0,0]
	v_mul_f32_e32 v68, 0x4b800000, v83
	v_cmp_gt_f32_e64 s[52:53], s29, v83
	v_mul_legacy_f32 v76, v71, v76
	v_cndmask_b32_e64 v77, 0, v77, s[50:51]
	v_cndmask_b32_e64 v68, v83, v68, s[52:53]
	v_rsq_f32_e32 v68, v68
	v_cndmask_b32_e64 v78, 0, v70, s[50:51]
	v_cmp_gt_f32_e64 s[50:51], s29, v82
	v_cndmask_b32_e64 v93, 0, v93, s[54:55]
	v_mul_f32_e32 v69, 0x45800000, v68
	v_cndmask_b32_e64 v83, v68, v69, s[52:53]
	v_cndmask_b32_e64 v83, 0, v83, s[48:49]
	v_mul_legacy_f32 v68, v44, v83
	v_mul_f32_e32 v44, v45, v83
	v_mul_f32_e32 v45, 0x4b800000, v82
	v_cndmask_b32_e64 v45, v82, v45, s[50:51]
	v_mul_legacy_f32 v191, v64, v83
	v_rsq_f32_e32 v45, v45
	v_mul_legacy_f32 v75, v65, v83
	v_mul_legacy_f32 v69, v60, v83
	v_mul_legacy_f32 v73, v66, v83
	v_mul_f32_e32 v64, v67, v83
	v_mul_legacy_f32 v67, v61, v83
	v_cndmask_b32_e64 v66, 0, v44, s[48:49]
	v_cndmask_b32_e64 v71, 0, v64, s[48:49]
	v_mul_legacy_f32 v65, v62, v83
	v_mul_legacy_f32 v64, v46, v83
	v_mul_legacy_f32 v61, v63, v83
	v_mul_legacy_f32 v60, v47, v83
	v_mul_f32_e32 v44, 0x45800000, v45
	v_cndmask_b32_e64 v44, v45, v44, s[50:51]
	v_mul_legacy_f32 v190, v56, v83
	v_mul_legacy_f32 v74, v57, v83
	v_cndmask_b32_e64 v44, 0, v44, s[46:47]
	v_mul_legacy_f32 v193, v52, v44
	v_mul_legacy_f32 v72, v58, v83
	v_mul_f32_e32 v56, v59, v83
	v_mul_legacy_f32 v59, v53, v44
	v_mul_legacy_f32 v57, v54, v44
	v_mul_legacy_f32 v55, v55, v44
	v_mul_legacy_f32 v53, v48, v44
	v_mul_legacy_f32 v49, v49, v44
	v_mul_legacy_f32 v192, v40, v44
	v_mul_legacy_f32 v47, v50, v44
	v_mul_f32_e32 v45, v51, v44
	v_mul_legacy_f32 v58, v41, v44
	v_add_f32_e32 v50, v137, v136
	v_add_f32_e32 v51, v138, v139
	v_add_f32_e32 v41, v50, v51
	v_add_f32_e32 v50, v133, v132
	v_add_f32_e32 v51, v134, v135
	v_add_f32_e32 v40, v50, v51
	ds_bpermute_b32 v51, v195, v41
	ds_bpermute_b32 v50, v195, v40
	v_cndmask_b32_e64 v70, 0, v56, s[48:49]
	v_mul_legacy_f32 v56, v42, v44
	s_waitcnt lgkmcnt(0)
	v_pk_add_f32 v[40:41], v[40:41], v[50:51]
	v_mul_legacy_f32 v54, v43, v44
	ds_bpermute_b32 v43, v196, v41
	ds_bpermute_b32 v42, v196, v40
	v_mul_legacy_f32 v52, v28, v44
	v_mul_legacy_f32 v48, v29, v44
	s_waitcnt lgkmcnt(0)
; __device__ __forceinline__ float bperm_f(int src_lane, float v) { return __builtin_bit_cast(float, __builtin_amdgcn_ds_bpermute(src_lane << 2, __builtin_bit_cast(int, v))); }
;     __device__ __forceinline__ void operator()(Acc& acc, const Unit& u, int wr, int wc, int fr, int fq) const {
;     ...
;           for (int q = 0; q < 8; ++q) {
;             const int t = tbase + 16 * q; const bool ok = (t >= 0) && (t < SEQ);
;             float sq = (pq[q][0] + pq[q][1]) + (pq[q][2] + pq[q][3]); sq += bperm_f(ln ^ 16, sq); sq += bperm_f(ln ^ 32, sq);
;             const float rs = rsqrtf(sq * (1.0f / DM) + EPS);
; #pragma unroll
;             for (int bj = 0; bj < 2; ++bj)
; #pragma unroll
;                 for (int n = 0; n < 2; ++n)
; #pragma unroll
;                     for (int i = 0; i < 4; ++i) { const float v = acc[q >> 2][bj][q & 3][n][i]; acc[q >> 2][bj][q & 3][n][i] = ok ? v * rs : 0.f; }
;           }
;     ...
;                 const int cg_ = ch0 + 4 * n + i, cv_ = DFF + cg_;
;                 const float g0 = cw[cg_], g1 = cw[NUP + cg_], g2 = cw[2 * NUP + cg_], gb = cb[cg_];
;                 const float v0 = cw[cv_], v1 = cw[NUP + cv_], v2 = cw[2 * NUP + cv_], vb = cb[cv_];
	v_pk_add_f32 v[28:29], v[40:41], v[42:43]
	v_pk_fma_f32 v[28:29], v[28:29], s[90:91], v[188:189] op_sel_hi:[1,0,0]
	v_mul_legacy_f32 v46, v30, v44
	v_mul_f32_e32 v40, 0x4b800000, v29
	v_cmp_gt_f32_e64 s[48:49], s29, v29
	v_mul_legacy_f32 v44, v31, v44
	v_cndmask_b32_e64 v29, v29, v40, s[48:49]
	v_rsq_f32_e32 v29, v29
	v_cndmask_b32_e64 v45, 0, v45, s[46:47]
	v_cmp_gt_f32_e64 s[46:47], s29, v28
	v_mul_f32_e32 v30, 0x45800000, v29
	v_cndmask_b32_e64 v40, v29, v30, s[48:49]
	v_mul_f32_e32 v29, v36, v40
	v_cndmask_b32_e64 v40, 0, v40, s[44:45]
	v_mul_legacy_f32 v36, v12, v40
	v_mul_f32_e32 v12, v13, v40
	v_mul_f32_e32 v13, 0x4b800000, v28
	v_cndmask_b32_e64 v133, 0, v29, s[44:45]
	v_cndmask_b32_e64 v13, v28, v13, s[46:47]
	v_mul_legacy_f32 v63, v37, v40
	v_rsq_f32_e32 v13, v13
	v_mul_legacy_f32 v43, v38, v40
	v_mul_legacy_f32 v39, v39, v40
	v_mul_f32_e32 v29, v32, v40
	v_cndmask_b32_e64 v32, 0, v12, s[44:45]
	v_mul_legacy_f32 v30, v14, v40
	v_mul_legacy_f32 v28, v15, v40
	v_mul_f32_e32 v12, 0x45800000, v13
	v_cndmask_b32_e64 v12, v13, v12, s[46:47]
	v_cndmask_b32_e32 v12, 0, v12, vcc
	v_mul_legacy_f32 v135, v20, v12
	v_mul_legacy_f32 v83, v21, v12
	v_cndmask_b32_e64 v37, 0, v29, s[44:45]
	v_mul_legacy_f32 v51, v22, v12
	v_mul_legacy_f32 v33, v33, v40
	v_mul_legacy_f32 v132, v24, v40
	v_mul_legacy_f32 v41, v23, v12
	v_mul_legacy_f32 v31, v34, v40
	v_mul_f32_e32 v29, v35, v40
	v_mul_legacy_f32 v62, v25, v40
	v_mul_legacy_f32 v35, v16, v12
	v_mul_legacy_f32 v134, v8, v12
	v_mul_legacy_f32 v34, v4, v12
	v_mul_legacy_f32 v42, v26, v40
	v_mul_f32_e32 v24, v27, v40
	v_mul_legacy_f32 v27, v17, v12
	v_mul_legacy_f32 v82, v9, v12
	v_mul_legacy_f32 v26, v5, v12
	v_mul_legacy_f32 v15, v18, v12
	v_mul_legacy_f32 v50, v10, v12
	v_mul_legacy_f32 v14, v6, v12
	v_cndmask_b32_e64 v29, 0, v29, s[44:45]
	v_cndmask_b32_e64 v38, 0, v24, s[44:45]
	v_mul_legacy_f32 v13, v19, v12
	v_mul_legacy_f32 v40, v11, v12
	v_mul_legacy_f32 v12, v7, v12
	v_lshl_or_b32 v4, s34, 7, v2
	v_ashrrev_i32_e32 v5, 31, v4
	v_lshlrev_b64 v[16:17], 2, v[4:5]
	v_lshl_add_u64 v[6:7], s[36:37], 0, v[16:17]
	s_movk_i32 s21, 0x5000
	v_add_co_u32_e32 v8, vcc, s21, v6
	s_mov_b32 s21, 0xb000
	s_nop 0
	v_addc_co_u32_e32 v9, vcc, 0, v7, vcc
	v_add_co_u32_e32 v10, vcc, s21, v6
	v_lshl_add_u64 v[16:17], s[60:61], 0, v[16:17]
	s_nop 0
	v_addc_co_u32_e32 v11, vcc, 0, v7, vcc
	global_load_dword v139, v[6:7], off
	global_load_dword v137, v[8:9], off offset:2048
	global_load_dword v136, v[10:11], off
	global_load_dword v189, v[16:17], off
	v_add_co_u32_e32 v18, vcc, s97, v6
	s_mov_b32 s21, 0xd000
	s_nop 0
	v_addc_co_u32_e32 v19, vcc, 0, v7, vcc
	v_add_co_u32_e32 v22, vcc, s80, v6
	global_load_dword v138, v[18:19], off offset:3072
	s_nop 0
	v_addc_co_u32_e32 v23, vcc, 0, v7, vcc
	v_add_co_u32_e32 v20, vcc, s97, v16
	s_nop 0
	s_nop 0
	v_addc_co_u32_e32 v21, vcc, 0, v17, vcc
	v_add_co_u32_e32 v24, vcc, s21, v6
	global_load_dword v188, v[20:21], off offset:3072
	s_nop 0
	v_addc_co_u32_e32 v25, vcc, 0, v7, vcc
	global_load_dword v229, v[22:23], off offset:1024
	global_load_dword v228, v[24:25], off offset:3072
	global_load_dword v232, v[6:7], off offset:4
	global_load_dword v233, v[8:9], off offset:2052
	global_load_dword v234, v[10:11], off offset:4
	global_load_dword v235, v[16:17], off offset:4
	global_load_dword v236, v[20:21], off offset:3076
	global_load_dword v237, v[18:19], off offset:3076
	global_load_dword v238, v[22:23], off offset:1028
	global_load_dword v239, v[24:25], off offset:3076
	s_nop 0
	v_mov_b32_dpp v111, v182 row_ror:1 row_mask:0xf bank_mask:0xf
	v_mov_b32_dpp v121, v182 row_ror:2 row_mask:0xf bank_mask:0xf
	v_cndmask_b32_e64 v183, v111, 0, s[38:39]
	v_cndmask_b32_e64 v155, 0, v121, s[40:41]
	v_mov_b32_dpp v123, v184 row_ror:1 row_mask:0xf bank_mask:0xf
	v_mov_b32_dpp v125, v184 row_ror:2 row_mask:0xf bank_mask:0xf
	v_cndmask_b32_e64 v185, v123, 0, s[38:39]
	v_cndmask_b32_e64 v159, 0, v125, s[40:41]
	s_waitcnt vmcnt(13)
	v_pk_mul_f32 v[182:183], v[136:137], v[182:183]
	s_waitcnt vmcnt(12)
	v_fma_f32 v155, v139, v155, v189
	v_add_f32_e32 v155, v183, v155
	v_add_f32_e32 v155, v182, v155
	v_mul_f32_e32 v161, 0xbfb8aa3b, v155
	v_exp_f32_e32 v161, v161
	v_mov_b32_e32 v183, v136
	v_add_f32_e32 v136, 1.0, v161
	v_rcp_f32_e32 v161, v136
	s_waitcnt vmcnt(10)
	v_fma_f32 v159, v138, v159, v188
	v_mul_f32_e32 v155, v155, v161
	s_waitcnt vmcnt(9)
	v_mov_b32_e32 v136, v229
	s_waitcnt vmcnt(8)
; __device__ __forceinline__ float sigmoidf_(float x) { return __builtin_amdgcn_rcpf(1.0f + __expf(-x)); }
; template <int N> __device__ __forceinline__ float dpp_ror(float v) { return __builtin_bit_cast(float, __builtin_amdgcn_update_dpp(0, __builtin_bit_cast(int, v), 0x120 + N, 0xf, 0xf, false)); }
;     __device__ __forceinline__ void operator()(Acc& acc, const Unit& u, int wr, int wc, int fr, int fq) const {
;     ...
;                 float pg1 = 0.f, pg2 = 0.f, pv1 = 0.f, pv2 = 0.f;
; #pragma unroll
;                 for (int q = 0; q < 8; ++q) {
;                     float cgv = acc[q >> 2][0][q & 3][n][i], cvv = acc[q >> 2][1][q & 3][n][i];
;                     asm volatile("" : "+v"(cgv), "+v"(cvv) : "v"(chain));
;                     const float tg1 = dpp_ror<1>(cgv), tg2 = dpp_ror<2>(cgv), tv1 = dpp_ror<1>(cvv), tv2 = dpp_ror<2>(cvv);
;                     const float sg1 = fr >= 1 ? tg1 : pg1, sg2 = fr >= 2 ? tg2 : pg2, sv1 = fr >= 1 ? tv1 : pv1, sv2 = fr >= 2 ? tv2 : pv2;
;                     const float gg = gb + g0 * sg2 + g1 * sg1 + g2 * cgv;
;                     const float vv = vb + v0 * sv2 + v1 * sv1 + v2 * cvv;
;                     chain = gg * sigmoidf_(gg) * vv; acc[q >> 2][0][q & 3][n][i] = chain;
;                     pg1 = tg1; pg2 = tg2; pv1 = tv1; pv2 = tv2;
;                 }
	v_pk_mul_f32 v[184:185], v[228:229], v[184:185]
	v_mov_b32_e32 v182, v228
	v_add_f32_e32 v159, v185, v159
	v_add_f32_e32 v159, v184, v159
	v_mul_f32_e32 v184, v159, v155
	v_mov_b32_dpp v129, v187 row_ror:2 row_mask:0xf bank_mask:0xf
	v_mov_b32_dpp v153, v186 row_ror:2 row_mask:0xf bank_mask:0xf
	v_mov_b32_dpp v127, v187 row_ror:1 row_mask:0xf bank_mask:0xf
	v_mov_b32_dpp v131, v186 row_ror:1 row_mask:0xf bank_mask:0xf
	v_cndmask_b32_e64 v231, v121, v129, s[40:41]
	v_cndmask_b32_e64 v230, v125, v153, s[40:41]
	v_cndmask_b32_e64 v229, v127, v111, s[38:39]
	v_cndmask_b32_e64 v228, v131, v123, s[38:39]
	v_pk_fma_f32 v[230:231], v[138:139], v[230:231], v[188:189]
	v_pk_fma_f32 v[228:229], v[136:137], v[228:229], v[230:231]
	v_pk_fma_f32 v[186:187], v[182:183], v[186:187], v[228:229]
	v_mul_f32_e32 v111, 0xbfb8aa3b, v187
	v_exp_f32_e32 v111, v111
	s_nop 0
	v_add_f32_e32 v111, 1.0, v111
	v_rcp_f32_e32 v111, v111
	s_nop 0
	v_mul_f32_e32 v111, v187, v111
	v_mul_f32_e32 v185, v186, v111
	v_mov_b32_dpp v123, v115 row_ror:2 row_mask:0xf bank_mask:0xf
	v_mov_b32_dpp v155, v114 row_ror:2 row_mask:0xf bank_mask:0xf
	v_mov_b32_dpp v121, v115 row_ror:1 row_mask:0xf bank_mask:0xf
	v_mov_b32_dpp v125, v114 row_ror:1 row_mask:0xf bank_mask:0xf
	v_cndmask_b32_e64 v229, v129, v123, s[40:41]
	v_cndmask_b32_e64 v228, v153, v155, s[40:41]
	v_cndmask_b32_e64 v187, v121, v127, s[38:39]
	v_cndmask_b32_e64 v186, v125, v131, s[38:39]
	v_pk_fma_f32 v[228:229], v[138:139], v[228:229], v[188:189]
	v_pk_fma_f32 v[186:187], v[136:137], v[186:187], v[228:229]
	v_pk_fma_f32 v[114:115], v[182:183], v[114:115], v[186:187]
	v_mul_f32_e32 v111, 0xbfb8aa3b, v115
	v_exp_f32_e32 v111, v111
	s_nop 0
	v_add_f32_e32 v111, 1.0, v111
	v_rcp_f32_e32 v111, v111
	s_nop 0
	v_mul_f32_e32 v111, v115, v111
	v_mul_f32_e32 v186, v114, v111
	v_mov_b32_dpp v129, v99 row_ror:2 row_mask:0xf bank_mask:0xf
	v_mov_b32_dpp v153, v98 row_ror:2 row_mask:0xf bank_mask:0xf
	v_mov_b32_dpp v127, v99 row_ror:1 row_mask:0xf bank_mask:0xf
	v_mov_b32_dpp v131, v98 row_ror:1 row_mask:0xf bank_mask:0xf
	v_cndmask_b32_e64 v229, v123, v129, s[40:41]
	v_cndmask_b32_e64 v228, v155, v153, s[40:41]
	v_cndmask_b32_e64 v115, v127, v121, s[38:39]
	v_cndmask_b32_e64 v114, v131, v125, s[38:39]
	v_pk_fma_f32 v[228:229], v[138:139], v[228:229], v[188:189]
	v_pk_fma_f32 v[114:115], v[136:137], v[114:115], v[228:229]
	v_pk_fma_f32 v[98:99], v[182:183], v[98:99], v[114:115]
	v_mul_f32_e32 v111, 0xbfb8aa3b, v99
	v_exp_f32_e32 v111, v111
	s_nop 0
	v_add_f32_e32 v111, 1.0, v111
	v_rcp_f32_e32 v111, v111
	s_nop 0
	v_mul_f32_e32 v99, v99, v111
	v_mul_f32_e32 v187, v98, v99
	v_mov_b32_dpp v123, v191 row_ror:2 row_mask:0xf bank_mask:0xf
	v_mov_b32_dpp v155, v190 row_ror:2 row_mask:0xf bank_mask:0xf
	v_mov_b32_dpp v121, v191 row_ror:1 row_mask:0xf bank_mask:0xf
	v_mov_b32_dpp v125, v190 row_ror:1 row_mask:0xf bank_mask:0xf
	v_cndmask_b32_e64 v115, v129, v123, s[40:41]
	v_cndmask_b32_e64 v114, v153, v155, s[40:41]
	v_cndmask_b32_e64 v99, v121, v127, s[38:39]
	v_cndmask_b32_e64 v98, v125, v131, s[38:39]
	v_pk_fma_f32 v[114:115], v[138:139], v[114:115], v[188:189]
	v_pk_fma_f32 v[98:99], v[136:137], v[98:99], v[114:115]
	v_pk_fma_f32 v[98:99], v[182:183], v[190:191], v[98:99]
	v_mul_f32_e32 v111, 0xbfb8aa3b, v99
	v_exp_f32_e32 v111, v111
	s_nop 0
	v_add_f32_e32 v111, 1.0, v111
	v_rcp_f32_e32 v111, v111
	s_nop 0
	v_mul_f32_e32 v99, v99, v111
	v_mul_f32_e32 v190, v98, v99
	v_mov_b32_dpp v129, v193 row_ror:2 row_mask:0xf bank_mask:0xf
	v_mov_b32_dpp v153, v192 row_ror:2 row_mask:0xf bank_mask:0xf
	v_mov_b32_dpp v127, v193 row_ror:1 row_mask:0xf bank_mask:0xf
	v_mov_b32_dpp v131, v192 row_ror:1 row_mask:0xf bank_mask:0xf
	v_cndmask_b32_e64 v115, v123, v129, s[40:41]
	v_cndmask_b32_e64 v114, v155, v153, s[40:41]
	v_cndmask_b32_e64 v99, v127, v121, s[38:39]
	v_cndmask_b32_e64 v98, v131, v125, s[38:39]
	v_pk_fma_f32 v[114:115], v[138:139], v[114:115], v[188:189]
	v_pk_fma_f32 v[98:99], v[136:137], v[98:99], v[114:115]
	v_pk_fma_f32 v[98:99], v[182:183], v[192:193], v[98:99]
	v_mul_f32_e32 v111, 0xbfb8aa3b, v99
	v_exp_f32_e32 v111, v111
	s_nop 0
	v_add_f32_e32 v111, 1.0, v111
	v_rcp_f32_e32 v111, v111
	s_nop 0
	v_mul_f32_e32 v99, v99, v111
	v_mul_f32_e32 v191, v98, v99
	v_mov_b32_dpp v123, v133 row_ror:2 row_mask:0xf bank_mask:0xf
	v_mov_b32_dpp v155, v132 row_ror:2 row_mask:0xf bank_mask:0xf
	v_mov_b32_dpp v121, v133 row_ror:1 row_mask:0xf bank_mask:0xf
	v_mov_b32_dpp v125, v132 row_ror:1 row_mask:0xf bank_mask:0xf
	v_cndmask_b32_e64 v115, v129, v123, s[40:41]
	v_cndmask_b32_e64 v114, v153, v155, s[40:41]
	v_cndmask_b32_e64 v99, v121, v127, s[38:39]
	v_cndmask_b32_e64 v98, v125, v131, s[38:39]
	v_pk_fma_f32 v[114:115], v[138:139], v[114:115], v[188:189]
	v_pk_fma_f32 v[98:99], v[136:137], v[98:99], v[114:115]
	v_pk_fma_f32 v[98:99], v[182:183], v[132:133], v[98:99]
	v_mul_f32_e32 v111, 0xbfb8aa3b, v99
	v_exp_f32_e32 v111, v111
	s_nop 0
	v_add_f32_e32 v111, 1.0, v111
	v_rcp_f32_e32 v111, v111
	s_nop 0
	v_mul_f32_e32 v99, v99, v111
	v_mul_f32_e32 v192, v98, v99
	v_mov_b32_dpp v114, v135 row_ror:1 row_mask:0xf bank_mask:0xf
	v_mov_b32_dpp v115, v135 row_ror:2 row_mask:0xf bank_mask:0xf
	v_mov_b32_dpp v129, v134 row_ror:2 row_mask:0xf bank_mask:0xf
	v_mov_b32_dpp v127, v134 row_ror:1 row_mask:0xf bank_mask:0xf
	v_cndmask_b32_e64 v99, v114, v121, s[38:39]
	v_cndmask_b32_e64 v115, v123, v115, s[40:41]
	v_cndmask_b32_e64 v114, v155, v129, s[40:41]
	v_cndmask_b32_e64 v98, v127, v125, s[38:39]
	v_pk_fma_f32 v[114:115], v[138:139], v[114:115], v[188:189]
	s_nop 0
	v_pk_fma_f32 v[98:99], v[136:137], v[98:99], v[114:115]
	s_nop 0
	v_pk_fma_f32 v[98:99], v[182:183], v[134:135], v[98:99]
	s_nop 0
	v_mul_f32_e32 v111, 0xbfb8aa3b, v99
	v_exp_f32_e32 v111, v111
	s_nop 0
	v_add_f32_e32 v111, 1.0, v111
	v_rcp_f32_e32 v111, v111
	s_nop 0
	v_mul_f32_e32 v99, v99, v111
	v_mul_f32_e32 v136, v98, v99
	s_waitcnt vmcnt(0)
; __device__ __forceinline__ float sigmoidf_(float x) { return __builtin_amdgcn_rcpf(1.0f + __expf(-x)); }
; template <int N> __device__ __forceinline__ float dpp_ror(float v) { return __builtin_bit_cast(float, __builtin_amdgcn_update_dpp(0, __builtin_bit_cast(int, v), 0x120 + N, 0xf, 0xf, false)); }
;     __device__ __forceinline__ void operator()(Acc& acc, const Unit& u, int wr, int wc, int fr, int fq) const {
;     ...
;                 const float g0 = cw[cg_], g1 = cw[NUP + cg_], g2 = cw[2 * NUP + cg_], gb = cb[cg_];
;                 const float v0 = cw[cv_], v1 = cw[NUP + cv_], v2 = cw[2 * NUP + cv_], vb = cb[cv_];
;                 float pg1 = 0.f, pg2 = 0.f, pv1 = 0.f, pv2 = 0.f;
; #pragma unroll
;                 for (int q = 0; q < 8; ++q) {
;                     float cgv = acc[q >> 2][0][q & 3][n][i], cvv = acc[q >> 2][1][q & 3][n][i];
;                     asm volatile("" : "+v"(cgv), "+v"(cvv) : "v"(chain));
;                     const float tg1 = dpp_ror<1>(cgv), tg2 = dpp_ror<2>(cgv), tv1 = dpp_ror<1>(cvv), tv2 = dpp_ror<2>(cvv);
;                     const float sg1 = fr >= 1 ? tg1 : pg1, sg2 = fr >= 2 ? tg2 : pg2, sv1 = fr >= 1 ? tv1 : pv1, sv2 = fr >= 2 ? tv2 : pv2;
;                     const float gg = gb + g0 * sg2 + g1 * sg1 + g2 * cgv;
;                     const float vv = vb + v0 * sv2 + v1 * sv1 + v2 * cvv;
;                     chain = gg * sigmoidf_(gg) * vv; acc[q >> 2][0][q & 3][n][i] = chain;
;                     pg1 = tg1; pg2 = tg2; pv1 = tv1; pv2 = tv2;
;                 }
	v_mov_b32_e32 v115, v232
	v_mov_b32_e32 v99, v233
	v_mov_b32_e32 v98, v234
	v_mov_b32_e32 v133, v235
	v_mov_b32_e32 v132, v236
	v_mov_b32_e32 v114, v237
	v_mov_b32_e32 v139, v238
	v_mov_b32_e32 v138, v239
	global_load_dword v240, v[6:7], off offset:8
	global_load_dword v241, v[8:9], off offset:2056
	global_load_dword v242, v[10:11], off offset:8
	global_load_dword v243, v[16:17], off offset:8
	global_load_dword v244, v[20:21], off offset:3080
	global_load_dword v245, v[18:19], off offset:3080
	global_load_dword v246, v[22:23], off offset:1032
	global_load_dword v247, v[24:25], off offset:3080
	v_mov_b32_dpp v111, v176 row_ror:1 row_mask:0xf bank_mask:0xf
	v_mov_b32_dpp v121, v176 row_ror:2 row_mask:0xf bank_mask:0xf
	v_cndmask_b32_e64 v177, v111, 0, s[38:39]
	v_cndmask_b32_e64 v134, 0, v121, s[40:41]
	v_mov_b32_dpp v123, v178 row_ror:1 row_mask:0xf bank_mask:0xf
	v_cndmask_b32_e64 v179, v123, 0, s[38:39]
	v_mov_b32_dpp v125, v178 row_ror:2 row_mask:0xf bank_mask:0xf
	v_cndmask_b32_e64 v137, 0, v125, s[40:41]
	s_nop 0
	v_fma_f32 v155, v115, v134, v133
	v_pk_mul_f32 v[134:135], v[98:99], v[176:177]
	s_nop 0
	v_fma_f32 v137, v114, v137, v132
	v_add_f32_e32 v135, v135, v155
	v_add_f32_e32 v155, v134, v135
	v_mul_f32_e32 v134, 0xbfb8aa3b, v155
	v_exp_f32_e32 v159, v134
	v_mov_b32_e32 v135, v98
	s_nop 0
	v_pk_mul_f32 v[176:177], v[138:139], v[178:179]
	v_mov_b32_e32 v134, v138
	v_add_f32_e32 v98, 1.0, v159
	v_rcp_f32_e32 v138, v98
	v_add_f32_e32 v137, v177, v137
	v_add_f32_e32 v137, v176, v137
	v_mov_b32_e32 v98, v139
	v_mul_f32_e32 v138, v155, v138
	v_mul_f32_e32 v137, v137, v138
	v_mov_b32_dpp v129, v181 row_ror:2 row_mask:0xf bank_mask:0xf
	v_mov_b32_dpp v153, v180 row_ror:2 row_mask:0xf bank_mask:0xf
	v_mov_b32_dpp v127, v181 row_ror:1 row_mask:0xf bank_mask:0xf
	v_mov_b32_dpp v131, v180 row_ror:1 row_mask:0xf bank_mask:0xf
	v_cndmask_b32_e64 v177, v121, v129, s[40:41]
	v_cndmask_b32_e64 v176, v125, v153, s[40:41]
	v_cndmask_b32_e64 v139, v127, v111, s[38:39]
	v_cndmask_b32_e64 v138, v131, v123, s[38:39]
	v_pk_fma_f32 v[176:177], v[114:115], v[176:177], v[132:133]
	v_pk_fma_f32 v[138:139], v[98:99], v[138:139], v[176:177]
	v_pk_fma_f32 v[138:139], v[134:135], v[180:181], v[138:139]
	v_mul_f32_e32 v111, 0xbfb8aa3b, v139
	v_exp_f32_e32 v111, v111
	s_nop 0
	v_add_f32_e32 v111, 1.0, v111
	v_rcp_f32_e32 v111, v111
	s_nop 0
	v_mul_f32_e32 v111, v139, v111
	v_mul_f32_e32 v138, v138, v111
	v_mov_b32_dpp v123, v107 row_ror:2 row_mask:0xf bank_mask:0xf
	v_mov_b32_dpp v155, v106 row_ror:2 row_mask:0xf bank_mask:0xf
	v_mov_b32_dpp v121, v107 row_ror:1 row_mask:0xf bank_mask:0xf
	v_mov_b32_dpp v125, v106 row_ror:1 row_mask:0xf bank_mask:0xf
	v_cndmask_b32_e64 v179, v129, v123, s[40:41]
	v_cndmask_b32_e64 v178, v153, v155, s[40:41]
	v_cndmask_b32_e64 v177, v121, v127, s[38:39]
	v_cndmask_b32_e64 v176, v125, v131, s[38:39]
	v_pk_fma_f32 v[178:179], v[114:115], v[178:179], v[132:133]
	v_pk_fma_f32 v[176:177], v[98:99], v[176:177], v[178:179]
	v_pk_fma_f32 v[106:107], v[134:135], v[106:107], v[176:177]
	v_mul_f32_e32 v111, 0xbfb8aa3b, v107
	v_exp_f32_e32 v111, v111
	s_nop 0
	v_add_f32_e32 v111, 1.0, v111
	v_rcp_f32_e32 v111, v111
	s_nop 0
	v_mul_f32_e32 v107, v107, v111
	v_mul_f32_e32 v106, v106, v107
	v_mov_b32_dpp v129, v91 row_ror:2 row_mask:0xf bank_mask:0xf
	v_mov_b32_dpp v139, v90 row_ror:2 row_mask:0xf bank_mask:0xf
	v_mov_b32_dpp v127, v91 row_ror:1 row_mask:0xf bank_mask:0xf
	v_mov_b32_dpp v131, v90 row_ror:1 row_mask:0xf bank_mask:0xf
	v_cndmask_b32_e64 v179, v123, v129, s[40:41]
	v_cndmask_b32_e64 v178, v155, v139, s[40:41]
	v_cndmask_b32_e64 v177, v127, v121, s[38:39]
	v_cndmask_b32_e64 v176, v131, v125, s[38:39]
	v_pk_fma_f32 v[178:179], v[114:115], v[178:179], v[132:133]
	v_pk_fma_f32 v[176:177], v[98:99], v[176:177], v[178:179]
	v_pk_fma_f32 v[90:91], v[134:135], v[90:91], v[176:177]
	v_mul_f32_e32 v107, 0xbfb8aa3b, v91
	v_exp_f32_e32 v107, v107
	s_nop 0
	v_add_f32_e32 v107, 1.0, v107
	v_rcp_f32_e32 v107, v107
	s_nop 0
	v_mul_f32_e32 v91, v91, v107
	v_mul_f32_e32 v90, v90, v91
	v_mov_b32_dpp v121, v75 row_ror:2 row_mask:0xf bank_mask:0xf
	v_mov_b32_dpp v125, v74 row_ror:2 row_mask:0xf bank_mask:0xf
	v_mov_b32_dpp v111, v75 row_ror:1 row_mask:0xf bank_mask:0xf
	v_mov_b32_dpp v123, v74 row_ror:1 row_mask:0xf bank_mask:0xf
	v_cndmask_b32_e64 v179, v129, v121, s[40:41]
	v_cndmask_b32_e64 v178, v139, v125, s[40:41]
	v_cndmask_b32_e64 v177, v111, v127, s[38:39]
	v_cndmask_b32_e64 v176, v123, v131, s[38:39]
	v_pk_fma_f32 v[178:179], v[114:115], v[178:179], v[132:133]
	v_pk_fma_f32 v[176:177], v[98:99], v[176:177], v[178:179]
	v_pk_fma_f32 v[74:75], v[134:135], v[74:75], v[176:177]
	v_mul_f32_e32 v91, 0xbfb8aa3b, v75
	v_exp_f32_e32 v91, v91
	s_nop 0
	v_add_f32_e32 v91, 1.0, v91
	v_rcp_f32_e32 v91, v91
	s_nop 0
	v_mul_f32_e32 v75, v75, v91
	v_mul_f32_e32 v91, v74, v75
	v_mov_b32_dpp v129, v59 row_ror:2 row_mask:0xf bank_mask:0xf
	v_mov_b32_dpp v139, v58 row_ror:2 row_mask:0xf bank_mask:0xf
	v_mov_b32_dpp v127, v59 row_ror:1 row_mask:0xf bank_mask:0xf
	v_mov_b32_dpp v131, v58 row_ror:1 row_mask:0xf bank_mask:0xf
	v_cndmask_b32_e64 v177, v121, v129, s[40:41]
	v_cndmask_b32_e64 v176, v125, v139, s[40:41]
	v_cndmask_b32_e64 v75, v127, v111, s[38:39]
	v_cndmask_b32_e64 v74, v131, v123, s[38:39]
	v_pk_fma_f32 v[176:177], v[114:115], v[176:177], v[132:133]
	v_pk_fma_f32 v[74:75], v[98:99], v[74:75], v[176:177]
	v_pk_fma_f32 v[58:59], v[134:135], v[58:59], v[74:75]
	v_mul_f32_e32 v74, 0xbfb8aa3b, v59
	v_exp_f32_e32 v74, v74
	s_nop 0
	v_add_f32_e32 v74, 1.0, v74
	v_rcp_f32_e32 v74, v74
	s_nop 0
	v_mul_f32_e32 v59, v59, v74
	v_mul_f32_e32 v107, v58, v59
; __device__ __forceinline__ float sigmoidf_(float x) { return __builtin_amdgcn_rcpf(1.0f + __expf(-x)); }
; template <int N> __device__ __forceinline__ float dpp_ror(float v) { return __builtin_bit_cast(float, __builtin_amdgcn_update_dpp(0, __builtin_bit_cast(int, v), 0x120 + N, 0xf, 0xf, false)); }
;     __device__ __forceinline__ void operator()(Acc& acc, const Unit& u, int wr, int wc, int fr, int fq) const {
;     ...
;                 const float g0 = cw[cg_], g1 = cw[NUP + cg_], g2 = cw[2 * NUP + cg_], gb = cb[cg_];
;                 const float v0 = cw[cv_], v1 = cw[NUP + cv_], v2 = cw[2 * NUP + cv_], vb = cb[cv_];
;                 float pg1 = 0.f, pg2 = 0.f, pv1 = 0.f, pv2 = 0.f;
; #pragma unroll
;                 for (int q = 0; q < 8; ++q) {
;                     float cgv = acc[q >> 2][0][q & 3][n][i], cvv = acc[q >> 2][1][q & 3][n][i];
;                     asm volatile("" : "+v"(cgv), "+v"(cvv) : "v"(chain));
;                     const float tg1 = dpp_ror<1>(cgv), tg2 = dpp_ror<2>(cgv), tv1 = dpp_ror<1>(cvv), tv2 = dpp_ror<2>(cvv);
;                     const float sg1 = fr >= 1 ? tg1 : pg1, sg2 = fr >= 2 ? tg2 : pg2, sv1 = fr >= 1 ? tv1 : pv1, sv2 = fr >= 2 ? tv2 : pv2;
;                     const float gg = gb + g0 * sg2 + g1 * sg1 + g2 * cgv;
;                     const float vv = vb + v0 * sv2 + v1 * sv1 + v2 * cvv;
;                     chain = gg * sigmoidf_(gg) * vv; acc[q >> 2][0][q & 3][n][i] = chain;
;                     pg1 = tg1; pg2 = tg2; pv1 = tv1; pv2 = tv2;
;                 }
	v_mov_b32_dpp v121, v63 row_ror:2 row_mask:0xf bank_mask:0xf
	v_mov_b32_dpp v125, v62 row_ror:2 row_mask:0xf bank_mask:0xf
	v_mov_b32_dpp v111, v63 row_ror:1 row_mask:0xf bank_mask:0xf
	v_mov_b32_dpp v123, v62 row_ror:1 row_mask:0xf bank_mask:0xf
	v_cndmask_b32_e64 v75, v129, v121, s[40:41]
	v_cndmask_b32_e64 v74, v139, v125, s[40:41]
	v_cndmask_b32_e64 v59, v111, v127, s[38:39]
	v_cndmask_b32_e64 v58, v123, v131, s[38:39]
	v_pk_fma_f32 v[74:75], v[114:115], v[74:75], v[132:133]
	v_pk_fma_f32 v[58:59], v[98:99], v[58:59], v[74:75]
	v_pk_fma_f32 v[58:59], v[134:135], v[62:63], v[58:59]
	v_mul_f32_e32 v62, 0xbfb8aa3b, v59
	v_exp_f32_e32 v62, v62
	s_nop 0
	v_add_f32_e32 v62, 1.0, v62
	v_rcp_f32_e32 v62, v62
	s_nop 0
	v_mul_f32_e32 v59, v59, v62
	v_mul_f32_e32 v139, v58, v59
	v_mov_b32_dpp v63, v83 row_ror:1 row_mask:0xf bank_mask:0xf
	v_mov_b32_dpp v74, v83 row_ror:2 row_mask:0xf bank_mask:0xf
	v_mov_b32_dpp v127, v82 row_ror:2 row_mask:0xf bank_mask:0xf
	v_mov_b32_dpp v75, v82 row_ror:1 row_mask:0xf bank_mask:0xf
	v_cndmask_b32_e64 v59, v63, v111, s[38:39]
	v_cndmask_b32_e64 v63, v121, v74, s[40:41]
	v_cndmask_b32_e64 v62, v125, v127, s[40:41]
	v_cndmask_b32_e64 v58, v75, v123, s[38:39]
	v_pk_fma_f32 v[62:63], v[114:115], v[62:63], v[132:133]
	s_nop 0
	v_pk_fma_f32 v[58:59], v[98:99], v[58:59], v[62:63]
	s_nop 0
	v_pk_fma_f32 v[58:59], v[134:135], v[82:83], v[58:59]
	s_nop 0
	v_mul_f32_e32 v62, 0xbfb8aa3b, v59
	v_exp_f32_e32 v62, v62
	s_nop 0
	v_add_f32_e32 v62, 1.0, v62
	v_rcp_f32_e32 v62, v62
	s_nop 0
	v_mul_f32_e32 v59, v59, v62
	v_mul_f32_e32 v98, v58, v59
	s_waitcnt vmcnt(0)
	v_mov_b32_e32 v63, v240
	v_mov_b32_e32 v59, v241
	v_mov_b32_e32 v58, v242
	v_mov_b32_e32 v75, v243
	v_mov_b32_e32 v74, v244
	v_mov_b32_e32 v62, v245
	v_mov_b32_e32 v115, v246
	v_mov_b32_e32 v114, v247
	global_load_dword v232, v[6:7], off offset:12
	global_load_dword v233, v[8:9], off offset:2060
	global_load_dword v234, v[10:11], off offset:12
	global_load_dword v235, v[16:17], off offset:12
	global_load_dword v236, v[20:21], off offset:3084
	global_load_dword v237, v[18:19], off offset:3084
	global_load_dword v238, v[22:23], off offset:1036
	global_load_dword v239, v[24:25], off offset:3084
	v_mov_b32_dpp v111, v160 row_ror:1 row_mask:0xf bank_mask:0xf
	v_mov_b32_dpp v121, v160 row_ror:2 row_mask:0xf bank_mask:0xf
	v_cndmask_b32_e64 v161, v111, 0, s[38:39]
	v_cndmask_b32_e64 v82, 0, v121, s[40:41]
	v_mov_b32_dpp v123, v162 row_ror:1 row_mask:0xf bank_mask:0xf
	v_cndmask_b32_e64 v163, v123, 0, s[38:39]
	v_mov_b32_dpp v125, v162 row_ror:2 row_mask:0xf bank_mask:0xf
	v_cndmask_b32_e64 v99, 0, v125, s[40:41]
	s_nop 0
	v_fma_f32 v132, v63, v82, v75
	v_pk_mul_f32 v[82:83], v[58:59], v[160:161]
	s_nop 0
	v_fma_f32 v99, v62, v99, v74
	v_add_f32_e32 v83, v83, v132
	v_add_f32_e32 v135, v82, v83
	v_mul_f32_e32 v82, 0xbfb8aa3b, v135
	v_exp_f32_e32 v153, v82
	v_mov_b32_e32 v83, v58
	s_nop 0
	v_pk_mul_f32 v[132:133], v[114:115], v[162:163]
	v_mov_b32_e32 v82, v114
	v_add_f32_e32 v58, 1.0, v153
	v_rcp_f32_e32 v114, v58
	v_add_f32_e32 v99, v133, v99
	v_add_f32_e32 v99, v132, v99
	v_mov_b32_e32 v58, v115
	v_mul_f32_e32 v114, v135, v114
	v_mul_f32_e32 v99, v99, v114
	v_mov_b32_dpp v129, v175 row_ror:2 row_mask:0xf bank_mask:0xf
	v_mov_b32_dpp v134, v174 row_ror:2 row_mask:0xf bank_mask:0xf
	v_mov_b32_dpp v127, v175 row_ror:1 row_mask:0xf bank_mask:0xf
	v_mov_b32_dpp v131, v174 row_ror:1 row_mask:0xf bank_mask:0xf
	v_cndmask_b32_e64 v133, v121, v129, s[40:41]
	v_cndmask_b32_e64 v132, v125, v134, s[40:41]
	v_cndmask_b32_e64 v115, v127, v111, s[38:39]
	v_cndmask_b32_e64 v114, v131, v123, s[38:39]
	v_pk_fma_f32 v[132:133], v[62:63], v[132:133], v[74:75]
	v_pk_fma_f32 v[114:115], v[58:59], v[114:115], v[132:133]
	v_pk_fma_f32 v[114:115], v[82:83], v[174:175], v[114:115]
	v_mul_f32_e32 v111, 0xbfb8aa3b, v115
	v_exp_f32_e32 v111, v111
	s_nop 0
	v_add_f32_e32 v111, 1.0, v111
	v_rcp_f32_e32 v111, v111
	s_nop 0
	v_mul_f32_e32 v111, v115, v111
	v_mul_f32_e32 v114, v114, v111
	v_mov_b32_dpp v123, v105 row_ror:2 row_mask:0xf bank_mask:0xf
	v_mov_b32_dpp v153, v104 row_ror:2 row_mask:0xf bank_mask:0xf
	v_mov_b32_dpp v121, v105 row_ror:1 row_mask:0xf bank_mask:0xf
	v_mov_b32_dpp v125, v104 row_ror:1 row_mask:0xf bank_mask:0xf
	v_cndmask_b32_e64 v135, v129, v123, s[40:41]
	v_cndmask_b32_e64 v134, v134, v153, s[40:41]
	v_cndmask_b32_e64 v133, v121, v127, s[38:39]
	v_cndmask_b32_e64 v132, v125, v131, s[38:39]
	v_pk_fma_f32 v[134:135], v[62:63], v[134:135], v[74:75]
	v_pk_fma_f32 v[132:133], v[58:59], v[132:133], v[134:135]
	v_pk_fma_f32 v[104:105], v[82:83], v[104:105], v[132:133]
	v_mul_f32_e32 v111, 0xbfb8aa3b, v105
	v_exp_f32_e32 v111, v111
	s_nop 0
	v_add_f32_e32 v111, 1.0, v111
	v_rcp_f32_e32 v111, v111
	s_nop 0
	v_mul_f32_e32 v105, v105, v111
	v_mul_f32_e32 v104, v104, v105
	v_mov_b32_dpp v127, v89 row_ror:2 row_mask:0xf bank_mask:0xf
	v_mov_b32_dpp v131, v88 row_ror:2 row_mask:0xf bank_mask:0xf
	v_mov_b32_dpp v115, v89 row_ror:1 row_mask:0xf bank_mask:0xf
	v_mov_b32_dpp v129, v88 row_ror:1 row_mask:0xf bank_mask:0xf
	v_cndmask_b32_e64 v135, v123, v127, s[40:41]
	v_cndmask_b32_e64 v134, v153, v131, s[40:41]
	v_cndmask_b32_e64 v133, v115, v121, s[38:39]
	v_cndmask_b32_e64 v132, v129, v125, s[38:39]
	v_pk_fma_f32 v[134:135], v[62:63], v[134:135], v[74:75]
	v_pk_fma_f32 v[132:133], v[58:59], v[132:133], v[134:135]
	v_pk_fma_f32 v[88:89], v[82:83], v[88:89], v[132:133]
	v_mul_f32_e32 v105, 0xbfb8aa3b, v89
	v_exp_f32_e32 v105, v105
	s_nop 0
	v_add_f32_e32 v105, 1.0, v105
	v_rcp_f32_e32 v105, v105
	s_nop 0
	v_mul_f32_e32 v89, v89, v105
	v_mul_f32_e32 v88, v88, v89
; __device__ __forceinline__ float sigmoidf_(float x) { return __builtin_amdgcn_rcpf(1.0f + __expf(-x)); }
; template <int N> __device__ __forceinline__ float dpp_ror(float v) { return __builtin_bit_cast(float, __builtin_amdgcn_update_dpp(0, __builtin_bit_cast(int, v), 0x120 + N, 0xf, 0xf, false)); }
;     __device__ __forceinline__ void operator()(Acc& acc, const Unit& u, int wr, int wc, int fr, int fq) const {
;     ...
;                 const float g0 = cw[cg_], g1 = cw[NUP + cg_], g2 = cw[2 * NUP + cg_], gb = cb[cg_];
;                 const float v0 = cw[cv_], v1 = cw[NUP + cv_], v2 = cw[2 * NUP + cv_], vb = cb[cv_];
;                 float pg1 = 0.f, pg2 = 0.f, pv1 = 0.f, pv2 = 0.f;
; #pragma unroll
;                 for (int q = 0; q < 8; ++q) {
;                     float cgv = acc[q >> 2][0][q & 3][n][i], cvv = acc[q >> 2][1][q & 3][n][i];
;                     asm volatile("" : "+v"(cgv), "+v"(cvv) : "v"(chain));
;                     const float tg1 = dpp_ror<1>(cgv), tg2 = dpp_ror<2>(cgv), tv1 = dpp_ror<1>(cvv), tv2 = dpp_ror<2>(cvv);
;                     const float sg1 = fr >= 1 ? tg1 : pg1, sg2 = fr >= 2 ? tg2 : pg2, sv1 = fr >= 1 ? tv1 : pv1, sv2 = fr >= 2 ? tv2 : pv2;
;                     const float gg = gb + g0 * sg2 + g1 * sg1 + g2 * cgv;
;                     const float vv = vb + v0 * sv2 + v1 * sv1 + v2 * cvv;
;                     chain = gg * sigmoidf_(gg) * vv; acc[q >> 2][0][q & 3][n][i] = chain;
;                     pg1 = tg1; pg2 = tg2; pv1 = tv1; pv2 = tv2;
;                 }
	v_mov_b32_dpp v121, v73 row_ror:2 row_mask:0xf bank_mask:0xf
	v_mov_b32_dpp v125, v72 row_ror:2 row_mask:0xf bank_mask:0xf
	v_mov_b32_dpp v111, v73 row_ror:1 row_mask:0xf bank_mask:0xf
	v_mov_b32_dpp v123, v72 row_ror:1 row_mask:0xf bank_mask:0xf
	v_cndmask_b32_e64 v135, v127, v121, s[40:41]
	v_cndmask_b32_e64 v134, v131, v125, s[40:41]
	v_cndmask_b32_e64 v133, v111, v115, s[38:39]
	v_cndmask_b32_e64 v132, v123, v129, s[38:39]
	v_pk_fma_f32 v[134:135], v[62:63], v[134:135], v[74:75]
	v_pk_fma_f32 v[132:133], v[58:59], v[132:133], v[134:135]
	v_pk_fma_f32 v[72:73], v[82:83], v[72:73], v[132:133]
	v_mul_f32_e32 v89, 0xbfb8aa3b, v73
	v_exp_f32_e32 v89, v89
	s_nop 0
	v_add_f32_e32 v89, 1.0, v89
	v_rcp_f32_e32 v89, v89
	s_nop 0
	v_mul_f32_e32 v73, v73, v89
	v_mul_f32_e32 v72, v72, v73
	v_mov_b32_dpp v115, v57 row_ror:2 row_mask:0xf bank_mask:0xf
	v_mov_b32_dpp v129, v56 row_ror:2 row_mask:0xf bank_mask:0xf
	v_mov_b32_dpp v105, v57 row_ror:1 row_mask:0xf bank_mask:0xf
	v_mov_b32_dpp v127, v56 row_ror:1 row_mask:0xf bank_mask:0xf
	v_cndmask_b32_e64 v135, v121, v115, s[40:41]
	v_cndmask_b32_e64 v134, v125, v129, s[40:41]
	v_cndmask_b32_e64 v133, v105, v111, s[38:39]
	v_cndmask_b32_e64 v132, v127, v123, s[38:39]
	v_pk_fma_f32 v[134:135], v[62:63], v[134:135], v[74:75]
	v_pk_fma_f32 v[132:133], v[58:59], v[132:133], v[134:135]
	v_pk_fma_f32 v[56:57], v[82:83], v[56:57], v[132:133]
	v_mul_f32_e32 v73, 0xbfb8aa3b, v57
	v_exp_f32_e32 v73, v73
	s_nop 0
	v_add_f32_e32 v73, 1.0, v73
	v_rcp_f32_e32 v73, v73
	s_nop 0
	v_mul_f32_e32 v57, v57, v73
	v_mul_f32_e32 v73, v56, v57
	v_mov_b32_dpp v121, v43 row_ror:2 row_mask:0xf bank_mask:0xf
	v_mov_b32_dpp v125, v42 row_ror:2 row_mask:0xf bank_mask:0xf
	v_mov_b32_dpp v111, v43 row_ror:1 row_mask:0xf bank_mask:0xf
	v_mov_b32_dpp v123, v42 row_ror:1 row_mask:0xf bank_mask:0xf
	v_cndmask_b32_e64 v133, v115, v121, s[40:41]
	v_cndmask_b32_e64 v132, v129, v125, s[40:41]
	v_cndmask_b32_e64 v57, v111, v105, s[38:39]
	v_cndmask_b32_e64 v56, v123, v127, s[38:39]
	v_pk_fma_f32 v[132:133], v[62:63], v[132:133], v[74:75]
	v_pk_fma_f32 v[56:57], v[58:59], v[56:57], v[132:133]
	v_pk_fma_f32 v[42:43], v[82:83], v[42:43], v[56:57]
	v_mul_f32_e32 v56, 0xbfb8aa3b, v43
	v_exp_f32_e32 v56, v56
	s_nop 0
	v_add_f32_e32 v56, 1.0, v56
	v_rcp_f32_e32 v56, v56
	s_nop 0
	v_mul_f32_e32 v43, v43, v56
	v_mul_f32_e32 v89, v42, v43
	v_mov_b32_dpp v57, v51 row_ror:1 row_mask:0xf bank_mask:0xf
	v_mov_b32_dpp v105, v51 row_ror:2 row_mask:0xf bank_mask:0xf
	v_mov_b32_dpp v127, v50 row_ror:2 row_mask:0xf bank_mask:0xf
	v_mov_b32_dpp v115, v50 row_ror:1 row_mask:0xf bank_mask:0xf
	v_cndmask_b32_e64 v43, v57, v111, s[38:39]
	v_cndmask_b32_e64 v57, v121, v105, s[40:41]
	v_cndmask_b32_e64 v56, v125, v127, s[40:41]
	v_cndmask_b32_e64 v42, v115, v123, s[38:39]
	v_pk_fma_f32 v[56:57], v[62:63], v[56:57], v[74:75]
	s_nop 0
	v_pk_fma_f32 v[42:43], v[58:59], v[42:43], v[56:57]
	s_nop 0
	v_pk_fma_f32 v[42:43], v[82:83], v[50:51], v[42:43]
	s_nop 0
	v_mul_f32_e32 v50, 0xbfb8aa3b, v43
	v_exp_f32_e32 v50, v50
	s_nop 0
	v_add_f32_e32 v50, 1.0, v50
	v_rcp_f32_e32 v50, v50
	s_nop 0
	v_mul_f32_e32 v43, v43, v50
	v_mul_f32_e32 v62, v42, v43
	s_waitcnt vmcnt(0)
	v_mov_b32_e32 v51, v232
	v_mov_b32_e32 v43, v233
	v_mov_b32_e32 v42, v234
	v_mov_b32_e32 v57, v235
	v_mov_b32_e32 v56, v236
	v_mov_b32_e32 v50, v237
	v_mov_b32_e32 v75, v238
	v_mov_b32_e32 v74, v239
	global_load_dword v240, v[6:7], off offset:16
	global_load_dword v241, v[8:9], off offset:2064
	global_load_dword v242, v[10:11], off offset:16
	global_load_dword v243, v[16:17], off offset:16
	global_load_dword v244, v[20:21], off offset:3088
	global_load_dword v245, v[18:19], off offset:3088
	global_load_dword v246, v[22:23], off offset:1040
	global_load_dword v247, v[24:25], off offset:3088
	v_mov_b32_dpp v105, v154 row_ror:1 row_mask:0xf bank_mask:0xf
	v_mov_b32_dpp v111, v154 row_ror:2 row_mask:0xf bank_mask:0xf
	v_cndmask_b32_e64 v155, v105, 0, s[38:39]
	v_cndmask_b32_e64 v58, 0, v111, s[40:41]
	v_mov_b32_dpp v115, v158 row_ror:1 row_mask:0xf bank_mask:0xf
	v_cndmask_b32_e64 v159, v115, 0, s[38:39]
	v_mov_b32_dpp v121, v158 row_ror:2 row_mask:0xf bank_mask:0xf
	v_cndmask_b32_e64 v63, 0, v121, s[40:41]
	s_nop 0
	v_fma_f32 v82, v51, v58, v57
	v_pk_mul_f32 v[58:59], v[42:43], v[154:155]
	s_nop 0
	v_fma_f32 v63, v50, v63, v56
	v_add_f32_e32 v59, v59, v82
	v_add_f32_e32 v131, v58, v59
	v_mul_f32_e32 v58, 0xbfb8aa3b, v131
	v_exp_f32_e32 v132, v58
	v_mov_b32_e32 v59, v42
	s_nop 0
	v_pk_mul_f32 v[82:83], v[74:75], v[158:159]
	v_mov_b32_e32 v58, v74
	v_add_f32_e32 v42, 1.0, v132
	v_rcp_f32_e32 v74, v42
	v_add_f32_e32 v63, v83, v63
	v_add_f32_e32 v63, v82, v63
	v_mov_b32_e32 v42, v75
	v_mul_f32_e32 v74, v131, v74
	v_mul_f32_e32 v63, v63, v74
	v_mov_b32_dpp v125, v157 row_ror:2 row_mask:0xf bank_mask:0xf
	v_mov_b32_dpp v129, v156 row_ror:2 row_mask:0xf bank_mask:0xf
	v_mov_b32_dpp v123, v157 row_ror:1 row_mask:0xf bank_mask:0xf
	v_mov_b32_dpp v127, v156 row_ror:1 row_mask:0xf bank_mask:0xf
	v_cndmask_b32_e64 v83, v111, v125, s[40:41]
	v_cndmask_b32_e64 v82, v121, v129, s[40:41]
	v_cndmask_b32_e64 v75, v123, v105, s[38:39]
	v_cndmask_b32_e64 v74, v127, v115, s[38:39]
	v_pk_fma_f32 v[82:83], v[50:51], v[82:83], v[56:57]
	v_pk_fma_f32 v[74:75], v[42:43], v[74:75], v[82:83]
	v_pk_fma_f32 v[74:75], v[58:59], v[156:157], v[74:75]
	v_mul_f32_e32 v82, 0xbfb8aa3b, v75
	v_exp_f32_e32 v82, v82
	s_nop 0
	v_add_f32_e32 v82, 1.0, v82
	v_rcp_f32_e32 v82, v82
	s_nop 0
	v_mul_f32_e32 v75, v75, v82
	v_mul_f32_e32 v74, v74, v75
	v_mov_b32_dpp v111, v103 row_ror:2 row_mask:0xf bank_mask:0xf
	v_mov_b32_dpp v121, v102 row_ror:2 row_mask:0xf bank_mask:0xf
; __device__ __forceinline__ float sigmoidf_(float x) { return __builtin_amdgcn_rcpf(1.0f + __expf(-x)); }
; template <int N> __device__ __forceinline__ float dpp_ror(float v) { return __builtin_bit_cast(float, __builtin_amdgcn_update_dpp(0, __builtin_bit_cast(int, v), 0x120 + N, 0xf, 0xf, false)); }
;     __device__ __forceinline__ void operator()(Acc& acc, const Unit& u, int wr, int wc, int fr, int fq) const {
;     ...
;                 for (int q = 0; q < 8; ++q) {
;                     float cgv = acc[q >> 2][0][q & 3][n][i], cvv = acc[q >> 2][1][q & 3][n][i];
;                     asm volatile("" : "+v"(cgv), "+v"(cvv) : "v"(chain));
;                     const float tg1 = dpp_ror<1>(cgv), tg2 = dpp_ror<2>(cgv), tv1 = dpp_ror<1>(cvv), tv2 = dpp_ror<2>(cvv);
;                     const float sg1 = fr >= 1 ? tg1 : pg1, sg2 = fr >= 2 ? tg2 : pg2, sv1 = fr >= 1 ? tv1 : pv1, sv2 = fr >= 2 ? tv2 : pv2;
;                     const float gg = gb + g0 * sg2 + g1 * sg1 + g2 * cgv;
;                     const float vv = vb + v0 * sv2 + v1 * sv1 + v2 * cvv;
;                     chain = gg * sigmoidf_(gg) * vv; acc[q >> 2][0][q & 3][n][i] = chain;
;                     pg1 = tg1; pg2 = tg2; pv1 = tv1; pv2 = tv2;
;                 }
	v_mov_b32_dpp v105, v103 row_ror:1 row_mask:0xf bank_mask:0xf
	v_mov_b32_dpp v115, v102 row_ror:1 row_mask:0xf bank_mask:0xf
	v_cndmask_b32_e64 v133, v125, v111, s[40:41]
	v_cndmask_b32_e64 v132, v129, v121, s[40:41]
	v_cndmask_b32_e64 v83, v105, v123, s[38:39]
	v_cndmask_b32_e64 v82, v115, v127, s[38:39]
	v_pk_fma_f32 v[132:133], v[50:51], v[132:133], v[56:57]
	v_pk_fma_f32 v[82:83], v[42:43], v[82:83], v[132:133]
	v_pk_fma_f32 v[82:83], v[58:59], v[102:103], v[82:83]
	v_mul_f32_e32 v75, 0xbfb8aa3b, v83
	v_exp_f32_e32 v75, v75
	s_nop 0
	v_add_f32_e32 v75, 1.0, v75
	v_rcp_f32_e32 v75, v75
	s_nop 0
	v_mul_f32_e32 v75, v83, v75
	v_mul_f32_e32 v75, v82, v75
	v_mov_b32_dpp v125, v87 row_ror:2 row_mask:0xf bank_mask:0xf
	v_mov_b32_dpp v129, v86 row_ror:2 row_mask:0xf bank_mask:0xf
	v_mov_b32_dpp v123, v87 row_ror:1 row_mask:0xf bank_mask:0xf
	v_mov_b32_dpp v127, v86 row_ror:1 row_mask:0xf bank_mask:0xf
	v_cndmask_b32_e64 v103, v111, v125, s[40:41]
	v_cndmask_b32_e64 v102, v121, v129, s[40:41]
	v_cndmask_b32_e64 v83, v123, v105, s[38:39]
	v_cndmask_b32_e64 v82, v127, v115, s[38:39]
	v_pk_fma_f32 v[102:103], v[50:51], v[102:103], v[56:57]
	v_pk_fma_f32 v[82:83], v[42:43], v[82:83], v[102:103]
	v_pk_fma_f32 v[82:83], v[58:59], v[86:87], v[82:83]
	v_mul_f32_e32 v86, 0xbfb8aa3b, v83
	v_exp_f32_e32 v86, v86
	s_nop 0
	v_add_f32_e32 v86, 1.0, v86
	v_rcp_f32_e32 v86, v86
	s_nop 0
	v_mul_f32_e32 v83, v83, v86
	v_mul_f32_e32 v82, v82, v83
	v_mov_b32_dpp v111, v71 row_ror:2 row_mask:0xf bank_mask:0xf
	v_mov_b32_dpp v121, v70 row_ror:2 row_mask:0xf bank_mask:0xf
	v_mov_b32_dpp v105, v71 row_ror:1 row_mask:0xf bank_mask:0xf
	v_mov_b32_dpp v115, v70 row_ror:1 row_mask:0xf bank_mask:0xf
	v_cndmask_b32_e64 v103, v125, v111, s[40:41]
	v_cndmask_b32_e64 v102, v129, v121, s[40:41]
	v_cndmask_b32_e64 v87, v105, v123, s[38:39]
	v_cndmask_b32_e64 v86, v115, v127, s[38:39]
	v_pk_fma_f32 v[102:103], v[50:51], v[102:103], v[56:57]
	v_pk_fma_f32 v[86:87], v[42:43], v[86:87], v[102:103]
	v_pk_fma_f32 v[70:71], v[58:59], v[70:71], v[86:87]
	v_mul_f32_e32 v83, 0xbfb8aa3b, v71
	v_exp_f32_e32 v83, v83
	s_nop 0
	v_add_f32_e32 v83, 1.0, v83
	v_rcp_f32_e32 v83, v83
	s_nop 0
	v_mul_f32_e32 v71, v71, v83
	v_mul_f32_e32 v70, v70, v71
	v_mov_b32_dpp v125, v55 row_ror:2 row_mask:0xf bank_mask:0xf
	v_mov_b32_dpp v129, v54 row_ror:2 row_mask:0xf bank_mask:0xf
	v_mov_b32_dpp v123, v55 row_ror:1 row_mask:0xf bank_mask:0xf
	v_mov_b32_dpp v127, v54 row_ror:1 row_mask:0xf bank_mask:0xf
	v_cndmask_b32_e64 v103, v111, v125, s[40:41]
	v_cndmask_b32_e64 v102, v121, v129, s[40:41]
	v_cndmask_b32_e64 v87, v123, v105, s[38:39]
	v_cndmask_b32_e64 v86, v127, v115, s[38:39]
	v_pk_fma_f32 v[102:103], v[50:51], v[102:103], v[56:57]
	v_pk_fma_f32 v[86:87], v[42:43], v[86:87], v[102:103]
	v_pk_fma_f32 v[54:55], v[58:59], v[54:55], v[86:87]
	v_mul_f32_e32 v71, 0xbfb8aa3b, v55
	v_exp_f32_e32 v71, v71
	s_nop 0
	v_add_f32_e32 v71, 1.0, v71
	v_rcp_f32_e32 v71, v71
	s_nop 0
	v_mul_f32_e32 v55, v55, v71
	v_mul_f32_e32 v55, v54, v55
	v_mov_b32_dpp v105, v39 row_ror:2 row_mask:0xf bank_mask:0xf
	v_mov_b32_dpp v115, v38 row_ror:2 row_mask:0xf bank_mask:0xf
	v_mov_b32_dpp v83, v39 row_ror:1 row_mask:0xf bank_mask:0xf
	v_mov_b32_dpp v111, v38 row_ror:1 row_mask:0xf bank_mask:0xf
	v_cndmask_b32_e64 v103, v125, v105, s[40:41]
	v_cndmask_b32_e64 v102, v129, v115, s[40:41]
	v_cndmask_b32_e64 v87, v83, v123, s[38:39]
	v_cndmask_b32_e64 v86, v111, v127, s[38:39]
	v_pk_fma_f32 v[102:103], v[50:51], v[102:103], v[56:57]
	s_nop 0
	v_pk_fma_f32 v[86:87], v[42:43], v[86:87], v[102:103]
	v_pk_fma_f32 v[38:39], v[58:59], v[38:39], v[86:87]
	v_mul_f32_e32 v54, 0xbfb8aa3b, v39
	v_exp_f32_e32 v54, v54
	s_nop 0
	v_add_f32_e32 v54, 1.0, v54
	v_rcp_f32_e32 v54, v54
	s_nop 0
	v_mul_f32_e32 v39, v39, v54
	v_mul_f32_e32 v71, v38, v39
	v_mov_b32_dpp v86, v41 row_ror:1 row_mask:0xf bank_mask:0xf
	v_mov_b32_dpp v87, v41 row_ror:2 row_mask:0xf bank_mask:0xf
	v_mov_b32_dpp v103, v40 row_ror:2 row_mask:0xf bank_mask:0xf
	v_mov_b32_dpp v102, v40 row_ror:1 row_mask:0xf bank_mask:0xf
	v_cndmask_b32_e64 v39, v86, v83, s[38:39]
	v_cndmask_b32_e64 v87, v105, v87, s[40:41]
	v_cndmask_b32_e64 v86, v115, v103, s[40:41]
	v_cndmask_b32_e64 v38, v102, v111, s[38:39]
	v_pk_fma_f32 v[50:51], v[50:51], v[86:87], v[56:57]
	s_nop 0
	v_pk_fma_f32 v[38:39], v[42:43], v[38:39], v[50:51]
	s_nop 0
	v_pk_fma_f32 v[38:39], v[58:59], v[40:41], v[38:39]
	s_nop 0
	v_mul_f32_e32 v40, 0xbfb8aa3b, v39
	v_exp_f32_e32 v40, v40
	s_nop 0
	v_add_f32_e32 v40, 1.0, v40
	v_rcp_f32_e32 v40, v40
	s_nop 0
	v_mul_f32_e32 v39, v39, v40
	v_mul_f32_e32 v54, v38, v39
	s_waitcnt vmcnt(0)
; __device__ __forceinline__ float sigmoidf_(float x) { return __builtin_amdgcn_rcpf(1.0f + __expf(-x)); }
; template <int N> __device__ __forceinline__ float dpp_ror(float v) { return __builtin_bit_cast(float, __builtin_amdgcn_update_dpp(0, __builtin_bit_cast(int, v), 0x120 + N, 0xf, 0xf, false)); }
;     __device__ __forceinline__ void operator()(Acc& acc, const Unit& u, int wr, int wc, int fr, int fq) const {
;     ...
;                 const float g0 = cw[cg_], g1 = cw[NUP + cg_], g2 = cw[2 * NUP + cg_], gb = cb[cg_];
;                 const float v0 = cw[cv_], v1 = cw[NUP + cv_], v2 = cw[2 * NUP + cv_], vb = cb[cv_];
;                 float pg1 = 0.f, pg2 = 0.f, pv1 = 0.f, pv2 = 0.f;
; #pragma unroll
;                 for (int q = 0; q < 8; ++q) {
;                     float cgv = acc[q >> 2][0][q & 3][n][i], cvv = acc[q >> 2][1][q & 3][n][i];
;                     asm volatile("" : "+v"(cgv), "+v"(cvv) : "v"(chain));
;                     const float tg1 = dpp_ror<1>(cgv), tg2 = dpp_ror<2>(cgv), tv1 = dpp_ror<1>(cvv), tv2 = dpp_ror<2>(cvv);
;                     const float sg1 = fr >= 1 ? tg1 : pg1, sg2 = fr >= 2 ? tg2 : pg2, sv1 = fr >= 1 ? tv1 : pv1, sv2 = fr >= 2 ? tv2 : pv2;
;                     const float gg = gb + g0 * sg2 + g1 * sg1 + g2 * cgv;
;                     const float vv = vb + v0 * sv2 + v1 * sv1 + v2 * cvv;
;                     chain = gg * sigmoidf_(gg) * vv; acc[q >> 2][0][q & 3][n][i] = chain;
;                     pg1 = tg1; pg2 = tg2; pv1 = tv1; pv2 = tv2;
;                 }
	v_mov_b32_e32 v41, v240
	v_mov_b32_e32 v39, v241
	v_mov_b32_e32 v38, v242
	v_mov_b32_e32 v43, v243
	v_mov_b32_e32 v42, v244
	v_mov_b32_e32 v40, v245
	v_mov_b32_e32 v57, v246
	v_mov_b32_e32 v56, v247
	global_load_dword v232, v[6:7], off offset:20
	global_load_dword v233, v[8:9], off offset:2068
	global_load_dword v234, v[10:11], off offset:20
	global_load_dword v235, v[16:17], off offset:20
	global_load_dword v236, v[20:21], off offset:3092
	global_load_dword v237, v[18:19], off offset:3092
	global_load_dword v238, v[22:23], off offset:1044
	global_load_dword v239, v[24:25], off offset:3092
	v_mov_b32_dpp v83, v130 row_ror:1 row_mask:0xf bank_mask:0xf
	v_mov_b32_dpp v86, v130 row_ror:2 row_mask:0xf bank_mask:0xf
	v_cndmask_b32_e64 v131, v83, 0, s[38:39]
	v_cndmask_b32_e64 v50, 0, v86, s[40:41]
	v_mov_b32_dpp v87, v152 row_ror:1 row_mask:0xf bank_mask:0xf
	v_mov_b32_dpp v102, v152 row_ror:2 row_mask:0xf bank_mask:0xf
	v_cndmask_b32_e64 v153, v87, 0, s[38:39]
	v_cndmask_b32_e64 v58, 0, v102, s[40:41]
	s_nop 0
	v_fma_f32 v59, v41, v50, v43
	v_pk_mul_f32 v[50:51], v[38:39], v[130:131]
	s_nop 0
	v_fma_f32 v121, v40, v58, v42
	v_add_f32_e32 v51, v51, v59
	v_add_f32_e32 v123, v50, v51
	v_mul_f32_e32 v50, 0xbfb8aa3b, v123
	v_exp_f32_e32 v125, v50
	v_mov_b32_e32 v51, v38
	s_nop 0
	v_pk_mul_f32 v[58:59], v[56:57], v[152:153]
	v_mov_b32_e32 v50, v56
	v_add_f32_e32 v38, 1.0, v125
	v_rcp_f32_e32 v56, v38
	v_mov_b32_e32 v38, v57
	v_add_f32_e32 v57, v59, v121
	v_add_f32_e32 v57, v58, v57
	v_mul_f32_e32 v56, v123, v56
	v_mul_f32_e32 v56, v57, v56
	v_mov_b32_dpp v105, v119 row_ror:2 row_mask:0xf bank_mask:0xf
	v_mov_b32_dpp v111, v118 row_ror:1 row_mask:0xf bank_mask:0xf
	v_mov_b32_dpp v115, v118 row_ror:2 row_mask:0xf bank_mask:0xf
	v_mov_b32_dpp v103, v119 row_ror:1 row_mask:0xf bank_mask:0xf
	v_cndmask_b32_e64 v58, v111, v87, s[38:39]
	v_cndmask_b32_e64 v87, v86, v105, s[40:41]
	v_cndmask_b32_e64 v86, v102, v115, s[40:41]
	v_cndmask_b32_e64 v59, v103, v83, s[38:39]
	v_pk_fma_f32 v[86:87], v[40:41], v[86:87], v[42:43]
	v_pk_fma_f32 v[58:59], v[38:39], v[58:59], v[86:87]
	v_pk_fma_f32 v[58:59], v[50:51], v[118:119], v[58:59]
	v_mul_f32_e32 v57, 0xbfb8aa3b, v59
	v_exp_f32_e32 v57, v57
	s_nop 0
	v_add_f32_e32 v57, 1.0, v57
	v_rcp_f32_e32 v57, v57
	s_nop 0
	v_mul_f32_e32 v57, v59, v57
	v_mul_f32_e32 v57, v58, v57
	v_mov_b32_dpp v102, v101 row_ror:2 row_mask:0xf bank_mask:0xf
	v_mov_b32_dpp v119, v100 row_ror:2 row_mask:0xf bank_mask:0xf
	v_mov_b32_dpp v83, v101 row_ror:1 row_mask:0xf bank_mask:0xf
	v_mov_b32_dpp v118, v100 row_ror:1 row_mask:0xf bank_mask:0xf
	v_cndmask_b32_e64 v87, v105, v102, s[40:41]
	v_cndmask_b32_e64 v86, v115, v119, s[40:41]
	v_cndmask_b32_e64 v59, v83, v103, s[38:39]
	v_cndmask_b32_e64 v58, v118, v111, s[38:39]
	v_pk_fma_f32 v[86:87], v[40:41], v[86:87], v[42:43]
	v_pk_fma_f32 v[58:59], v[38:39], v[58:59], v[86:87]
	v_pk_fma_f32 v[58:59], v[50:51], v[100:101], v[58:59]
	v_mul_f32_e32 v86, 0xbfb8aa3b, v59
	v_exp_f32_e32 v86, v86
	s_nop 0
	v_add_f32_e32 v86, 1.0, v86
	v_rcp_f32_e32 v86, v86
	s_nop 0
	v_mul_f32_e32 v59, v59, v86
	v_mul_f32_e32 v58, v58, v59
	v_mov_b32_dpp v105, v85 row_ror:2 row_mask:0xf bank_mask:0xf
	v_mov_b32_dpp v115, v84 row_ror:2 row_mask:0xf bank_mask:0xf
	v_mov_b32_dpp v103, v85 row_ror:1 row_mask:0xf bank_mask:0xf
	v_mov_b32_dpp v111, v84 row_ror:1 row_mask:0xf bank_mask:0xf
	v_cndmask_b32_e64 v101, v102, v105, s[40:41]
	v_cndmask_b32_e64 v100, v119, v115, s[40:41]
	v_cndmask_b32_e64 v87, v103, v83, s[38:39]
	v_cndmask_b32_e64 v86, v111, v118, s[38:39]
	v_pk_fma_f32 v[100:101], v[40:41], v[100:101], v[42:43]
	v_pk_fma_f32 v[86:87], v[38:39], v[86:87], v[100:101]
	v_pk_fma_f32 v[84:85], v[50:51], v[84:85], v[86:87]
	v_mul_f32_e32 v59, 0xbfb8aa3b, v85
	v_exp_f32_e32 v59, v59
	s_nop 0
	v_add_f32_e32 v59, 1.0, v59
	v_rcp_f32_e32 v59, v59
	s_nop 0
	v_mul_f32_e32 v59, v85, v59
	v_mul_f32_e32 v59, v84, v59
	v_mov_b32_dpp v100, v69 row_ror:2 row_mask:0xf bank_mask:0xf
	v_mov_b32_dpp v102, v68 row_ror:2 row_mask:0xf bank_mask:0xf
	v_mov_b32_dpp v83, v69 row_ror:1 row_mask:0xf bank_mask:0xf
	v_mov_b32_dpp v101, v68 row_ror:1 row_mask:0xf bank_mask:0xf
	v_cndmask_b32_e64 v87, v105, v100, s[40:41]
	v_cndmask_b32_e64 v86, v115, v102, s[40:41]
	v_cndmask_b32_e64 v85, v83, v103, s[38:39]
	v_cndmask_b32_e64 v84, v101, v111, s[38:39]
	v_pk_fma_f32 v[86:87], v[40:41], v[86:87], v[42:43]
	v_pk_fma_f32 v[84:85], v[38:39], v[84:85], v[86:87]
	v_pk_fma_f32 v[68:69], v[50:51], v[68:69], v[84:85]
	v_mul_f32_e32 v84, 0xbfb8aa3b, v69
	v_exp_f32_e32 v84, v84
	s_nop 0
	v_add_f32_e32 v84, 1.0, v84
	v_rcp_f32_e32 v84, v84
	s_nop 0
	v_mul_f32_e32 v69, v69, v84
	v_mul_f32_e32 v68, v68, v69
	v_mov_b32_dpp v105, v53 row_ror:2 row_mask:0xf bank_mask:0xf
	v_mov_b32_dpp v115, v52 row_ror:2 row_mask:0xf bank_mask:0xf
	v_mov_b32_dpp v103, v53 row_ror:1 row_mask:0xf bank_mask:0xf
	v_mov_b32_dpp v111, v52 row_ror:1 row_mask:0xf bank_mask:0xf
	v_cndmask_b32_e64 v87, v100, v105, s[40:41]
	v_cndmask_b32_e64 v86, v102, v115, s[40:41]
	v_cndmask_b32_e64 v85, v103, v83, s[38:39]
	v_cndmask_b32_e64 v84, v111, v101, s[38:39]
	v_pk_fma_f32 v[86:87], v[40:41], v[86:87], v[42:43]
	v_pk_fma_f32 v[84:85], v[38:39], v[84:85], v[86:87]
	v_pk_fma_f32 v[52:53], v[50:51], v[52:53], v[84:85]
	v_mul_f32_e32 v69, 0xbfb8aa3b, v53
	v_exp_f32_e32 v69, v69
	s_nop 0
	v_add_f32_e32 v69, 1.0, v69
	v_rcp_f32_e32 v69, v69
	s_nop 0
	v_mul_f32_e32 v53, v53, v69
	v_mul_f32_e32 v52, v52, v53
	v_mov_b32_dpp v100, v37 row_ror:2 row_mask:0xf bank_mask:0xf
	v_mov_b32_dpp v102, v36 row_ror:2 row_mask:0xf bank_mask:0xf
	v_mov_b32_dpp v83, v37 row_ror:1 row_mask:0xf bank_mask:0xf
	v_mov_b32_dpp v101, v36 row_ror:1 row_mask:0xf bank_mask:0xf
	v_cndmask_b32_e64 v87, v105, v100, s[40:41]
	v_cndmask_b32_e64 v86, v115, v102, s[40:41]
	v_cndmask_b32_e64 v85, v83, v103, s[38:39]
	v_cndmask_b32_e64 v84, v101, v111, s[38:39]
	v_pk_fma_f32 v[86:87], v[40:41], v[86:87], v[42:43]
	s_nop 0
	v_pk_fma_f32 v[84:85], v[38:39], v[84:85], v[86:87]
	v_pk_fma_f32 v[36:37], v[50:51], v[36:37], v[84:85]
	v_mul_f32_e32 v53, 0xbfb8aa3b, v37
	v_exp_f32_e32 v53, v53
	s_nop 0
	v_add_f32_e32 v53, 1.0, v53
	v_rcp_f32_e32 v53, v53
	s_nop 0
	v_mul_f32_e32 v37, v37, v53
	v_mul_f32_e32 v53, v36, v37
	v_mov_b32_dpp v84, v35 row_ror:2 row_mask:0xf bank_mask:0xf
	v_mov_b32_dpp v85, v34 row_ror:1 row_mask:0xf bank_mask:0xf
	v_mov_b32_dpp v86, v34 row_ror:2 row_mask:0xf bank_mask:0xf
	v_mov_b32_dpp v69, v35 row_ror:1 row_mask:0xf bank_mask:0xf
	v_cndmask_b32_e64 v36, v85, v101, s[38:39]
	v_cndmask_b32_e64 v85, v100, v84, s[40:41]
	v_cndmask_b32_e64 v84, v102, v86, s[40:41]
	v_cndmask_b32_e64 v37, v69, v83, s[38:39]
	v_pk_fma_f32 v[40:41], v[40:41], v[84:85], v[42:43]
	s_nop 0
	v_pk_fma_f32 v[36:37], v[38:39], v[36:37], v[40:41]
	s_nop 0
	v_pk_fma_f32 v[34:35], v[50:51], v[34:35], v[36:37]
	s_nop 0
	v_mul_f32_e32 v36, 0xbfb8aa3b, v35
	v_exp_f32_e32 v36, v36
	s_nop 0
	v_add_f32_e32 v36, 1.0, v36
	v_rcp_f32_e32 v36, v36
	s_nop 0
	v_mul_f32_e32 v35, v35, v36
	v_mul_f32_e32 v42, v34, v35
	s_waitcnt vmcnt(0)
; __device__ __forceinline__ float sigmoidf_(float x) { return __builtin_amdgcn_rcpf(1.0f + __expf(-x)); }
; template <int N> __device__ __forceinline__ float dpp_ror(float v) { return __builtin_bit_cast(float, __builtin_amdgcn_update_dpp(0, __builtin_bit_cast(int, v), 0x120 + N, 0xf, 0xf, false)); }
;     __device__ __forceinline__ void operator()(Acc& acc, const Unit& u, int wr, int wc, int fr, int fq) const {
;     ...
;                 const float g0 = cw[cg_], g1 = cw[NUP + cg_], g2 = cw[2 * NUP + cg_], gb = cb[cg_];
;                 const float v0 = cw[cv_], v1 = cw[NUP + cv_], v2 = cw[2 * NUP + cv_], vb = cb[cv_];
;                 float pg1 = 0.f, pg2 = 0.f, pv1 = 0.f, pv2 = 0.f;
; #pragma unroll
;                 for (int q = 0; q < 8; ++q) {
;                     float cgv = acc[q >> 2][0][q & 3][n][i], cvv = acc[q >> 2][1][q & 3][n][i];
;                     asm volatile("" : "+v"(cgv), "+v"(cvv) : "v"(chain));
;                     const float tg1 = dpp_ror<1>(cgv), tg2 = dpp_ror<2>(cgv), tv1 = dpp_ror<1>(cvv), tv2 = dpp_ror<2>(cvv);
;                     const float sg1 = fr >= 1 ? tg1 : pg1, sg2 = fr >= 2 ? tg2 : pg2, sv1 = fr >= 1 ? tv1 : pv1, sv2 = fr >= 2 ? tv2 : pv2;
;                     const float gg = gb + g0 * sg2 + g1 * sg1 + g2 * cgv;
;                     const float vv = vb + v0 * sv2 + v1 * sv1 + v2 * cvv;
;                     chain = gg * sigmoidf_(gg) * vv; acc[q >> 2][0][q & 3][n][i] = chain;
;                     pg1 = tg1; pg2 = tg2; pv1 = tv1; pv2 = tv2;
;                 }
	v_mov_b32_e32 v37, v232
	v_mov_b32_e32 v35, v233
	v_mov_b32_e32 v34, v234
	v_mov_b32_e32 v39, v235
	v_mov_b32_e32 v38, v236
	v_mov_b32_e32 v36, v237
	v_mov_b32_e32 v51, v238
	v_mov_b32_e32 v50, v239
	global_load_dword v240, v[6:7], off offset:24
	global_load_dword v241, v[8:9], off offset:2072
	global_load_dword v242, v[10:11], off offset:24
	global_load_dword v243, v[16:17], off offset:24
	global_load_dword v244, v[20:21], off offset:3096
	global_load_dword v245, v[18:19], off offset:3096
	global_load_dword v246, v[22:23], off offset:1048
	global_load_dword v247, v[24:25], off offset:3096
	v_mov_b32_dpp v69, v126 row_ror:1 row_mask:0xf bank_mask:0xf
	v_mov_b32_dpp v83, v126 row_ror:2 row_mask:0xf bank_mask:0xf
	v_cndmask_b32_e64 v127, v69, 0, s[38:39]
	v_cndmask_b32_e64 v40, 0, v83, s[40:41]
	v_mov_b32_dpp v86, v128 row_ror:1 row_mask:0xf bank_mask:0xf
	v_cndmask_b32_e64 v129, v86, 0, s[38:39]
	v_mov_b32_dpp v87, v128 row_ror:2 row_mask:0xf bank_mask:0xf
	v_cndmask_b32_e64 v43, 0, v87, s[40:41]
	s_nop 0
	v_fma_f32 v84, v37, v40, v39
	v_pk_mul_f32 v[40:41], v[34:35], v[126:127]
	s_nop 0
	v_fma_f32 v43, v36, v43, v38
	v_add_f32_e32 v41, v41, v84
	v_add_f32_e32 v105, v40, v41
	v_mul_f32_e32 v40, 0xbfb8aa3b, v105
	v_exp_f32_e32 v111, v40
	v_mov_b32_e32 v41, v34
	s_nop 0
	v_pk_mul_f32 v[84:85], v[50:51], v[128:129]
	v_mov_b32_e32 v40, v50
	v_add_f32_e32 v34, 1.0, v111
	v_rcp_f32_e32 v50, v34
	v_add_f32_e32 v43, v85, v43
	v_add_f32_e32 v43, v84, v43
	v_mov_b32_e32 v34, v51
	v_mul_f32_e32 v50, v105, v50
	v_mul_f32_e32 v43, v43, v50
	v_mov_b32_dpp v101, v117 row_ror:2 row_mask:0xf bank_mask:0xf
	v_mov_b32_dpp v103, v116 row_ror:2 row_mask:0xf bank_mask:0xf
	v_mov_b32_dpp v100, v117 row_ror:1 row_mask:0xf bank_mask:0xf
	v_mov_b32_dpp v102, v116 row_ror:1 row_mask:0xf bank_mask:0xf
	v_cndmask_b32_e64 v85, v83, v101, s[40:41]
	v_cndmask_b32_e64 v84, v87, v103, s[40:41]
	v_cndmask_b32_e64 v51, v100, v69, s[38:39]
	v_cndmask_b32_e64 v50, v102, v86, s[38:39]
	v_pk_fma_f32 v[84:85], v[36:37], v[84:85], v[38:39]
	v_pk_fma_f32 v[50:51], v[34:35], v[50:51], v[84:85]
	s_nop 0
	v_pk_fma_f32 v[50:51], v[40:41], v[116:117], v[50:51]
	s_nop 0
	v_mul_f32_e32 v69, 0xbfb8aa3b, v51
	v_exp_f32_e32 v69, v69
	s_nop 0
	v_add_f32_e32 v69, 1.0, v69
	v_rcp_f32_e32 v69, v69
	s_nop 0
	v_mul_f32_e32 v51, v51, v69
	v_mul_f32_e32 v50, v50, v51
	v_mov_b32_dpp v105, v97 row_ror:2 row_mask:0xf bank_mask:0xf
	v_mov_b32_dpp v115, v96 row_ror:2 row_mask:0xf bank_mask:0xf
	v_mov_b32_dpp v83, v97 row_ror:1 row_mask:0xf bank_mask:0xf
	v_mov_b32_dpp v111, v96 row_ror:1 row_mask:0xf bank_mask:0xf
	v_cndmask_b32_e64 v87, v101, v105, s[40:41]
	v_cndmask_b32_e64 v86, v103, v115, s[40:41]
	v_cndmask_b32_e64 v85, v83, v100, s[38:39]
	v_cndmask_b32_e64 v84, v111, v102, s[38:39]
	v_pk_fma_f32 v[86:87], v[36:37], v[86:87], v[38:39]
	v_pk_fma_f32 v[84:85], v[34:35], v[84:85], v[86:87]
	v_pk_fma_f32 v[84:85], v[40:41], v[96:97], v[84:85]
	v_mul_f32_e32 v51, 0xbfb8aa3b, v85
	v_exp_f32_e32 v51, v51
	s_nop 0
	v_add_f32_e32 v51, 1.0, v51
	v_rcp_f32_e32 v51, v51
	s_nop 0
	v_mul_f32_e32 v51, v85, v51
	v_mul_f32_e32 v51, v84, v51
	v_mov_b32_dpp v97, v81 row_ror:2 row_mask:0xf bank_mask:0xf
	v_mov_b32_dpp v101, v80 row_ror:2 row_mask:0xf bank_mask:0xf
	v_mov_b32_dpp v96, v81 row_ror:1 row_mask:0xf bank_mask:0xf
	v_mov_b32_dpp v100, v80 row_ror:1 row_mask:0xf bank_mask:0xf
	v_cndmask_b32_e64 v87, v105, v97, s[40:41]
	v_cndmask_b32_e64 v86, v115, v101, s[40:41]
	v_cndmask_b32_e64 v85, v96, v83, s[38:39]
	v_cndmask_b32_e64 v84, v100, v111, s[38:39]
	v_pk_fma_f32 v[86:87], v[36:37], v[86:87], v[38:39]
	v_pk_fma_f32 v[84:85], v[34:35], v[84:85], v[86:87]
	v_pk_fma_f32 v[80:81], v[40:41], v[80:81], v[84:85]
	v_mul_f32_e32 v69, 0xbfb8aa3b, v81
	v_exp_f32_e32 v69, v69
	s_nop 0
	v_add_f32_e32 v69, 1.0, v69
	v_rcp_f32_e32 v69, v69
	s_nop 0
	v_mul_f32_e32 v69, v81, v69
	v_mul_f32_e32 v69, v80, v69
	v_mov_b32_dpp v86, v67 row_ror:2 row_mask:0xf bank_mask:0xf
	v_mov_b32_dpp v102, v66 row_ror:2 row_mask:0xf bank_mask:0xf
	v_mov_b32_dpp v83, v67 row_ror:1 row_mask:0xf bank_mask:0xf
	v_mov_b32_dpp v87, v66 row_ror:1 row_mask:0xf bank_mask:0xf
	v_cndmask_b32_e64 v85, v97, v86, s[40:41]
	v_cndmask_b32_e64 v84, v101, v102, s[40:41]
	v_cndmask_b32_e64 v81, v83, v96, s[38:39]
	v_cndmask_b32_e64 v80, v87, v100, s[38:39]
	v_pk_fma_f32 v[84:85], v[36:37], v[84:85], v[38:39]
	v_pk_fma_f32 v[80:81], v[34:35], v[80:81], v[84:85]
	v_pk_fma_f32 v[66:67], v[40:41], v[66:67], v[80:81]
	v_mul_f32_e32 v80, 0xbfb8aa3b, v67
	v_exp_f32_e32 v80, v80
	s_nop 0
	v_add_f32_e32 v80, 1.0, v80
	v_rcp_f32_e32 v80, v80
	s_nop 0
	v_mul_f32_e32 v67, v67, v80
	v_mul_f32_e32 v66, v66, v67
	v_mov_b32_dpp v97, v49 row_ror:2 row_mask:0xf bank_mask:0xf
	v_mov_b32_dpp v101, v48 row_ror:2 row_mask:0xf bank_mask:0xf
	v_mov_b32_dpp v96, v49 row_ror:1 row_mask:0xf bank_mask:0xf
	v_mov_b32_dpp v100, v48 row_ror:1 row_mask:0xf bank_mask:0xf
	v_cndmask_b32_e64 v85, v86, v97, s[40:41]
	v_cndmask_b32_e64 v84, v102, v101, s[40:41]
	v_cndmask_b32_e64 v81, v96, v83, s[38:39]
	v_cndmask_b32_e64 v80, v100, v87, s[38:39]
	v_pk_fma_f32 v[84:85], v[36:37], v[84:85], v[38:39]
	v_pk_fma_f32 v[80:81], v[34:35], v[80:81], v[84:85]
	v_pk_fma_f32 v[48:49], v[40:41], v[48:49], v[80:81]
	v_mul_f32_e32 v67, 0xbfb8aa3b, v49
	v_exp_f32_e32 v67, v67
	s_nop 0
	v_add_f32_e32 v67, 1.0, v67
	v_rcp_f32_e32 v67, v67
	s_nop 0
	v_mul_f32_e32 v49, v49, v67
	v_mul_f32_e32 v48, v48, v49
	v_mov_b32_dpp v86, v33 row_ror:2 row_mask:0xf bank_mask:0xf
	v_mov_b32_dpp v102, v32 row_ror:2 row_mask:0xf bank_mask:0xf
	v_mov_b32_dpp v83, v33 row_ror:1 row_mask:0xf bank_mask:0xf
	v_mov_b32_dpp v87, v32 row_ror:1 row_mask:0xf bank_mask:0xf
	v_cndmask_b32_e64 v85, v97, v86, s[40:41]
	v_cndmask_b32_e64 v84, v101, v102, s[40:41]
	v_cndmask_b32_e64 v81, v83, v96, s[38:39]
	v_cndmask_b32_e64 v80, v87, v100, s[38:39]
	v_pk_fma_f32 v[84:85], v[36:37], v[84:85], v[38:39]
	s_nop 0
	v_pk_fma_f32 v[80:81], v[34:35], v[80:81], v[84:85]
	v_pk_fma_f32 v[32:33], v[40:41], v[32:33], v[80:81]
	v_mul_f32_e32 v49, 0xbfb8aa3b, v33
	v_exp_f32_e32 v49, v49
	s_nop 0
	v_add_f32_e32 v49, 1.0, v49
	v_rcp_f32_e32 v49, v49
	s_nop 0
	v_mul_f32_e32 v33, v33, v49
	v_mul_f32_e32 v49, v32, v33
	v_mov_b32_dpp v80, v27 row_ror:2 row_mask:0xf bank_mask:0xf
	v_mov_b32_dpp v81, v26 row_ror:1 row_mask:0xf bank_mask:0xf
	v_mov_b32_dpp v84, v26 row_ror:2 row_mask:0xf bank_mask:0xf
	v_mov_b32_dpp v67, v27 row_ror:1 row_mask:0xf bank_mask:0xf
	v_cndmask_b32_e64 v32, v81, v87, s[38:39]
	v_cndmask_b32_e64 v81, v86, v80, s[40:41]
	v_cndmask_b32_e64 v80, v102, v84, s[40:41]
	v_cndmask_b32_e64 v33, v67, v83, s[38:39]
	v_pk_fma_f32 v[36:37], v[36:37], v[80:81], v[38:39]
	s_nop 0
	v_pk_fma_f32 v[32:33], v[34:35], v[32:33], v[36:37]
	s_nop 0
	v_pk_fma_f32 v[26:27], v[40:41], v[26:27], v[32:33]
	s_nop 0
	v_mul_f32_e32 v32, 0xbfb8aa3b, v27
	v_exp_f32_e32 v32, v32
	s_nop 0
	v_add_f32_e32 v32, 1.0, v32
	v_rcp_f32_e32 v32, v32
	s_nop 0
	v_mul_f32_e32 v27, v27, v32
	v_mul_f32_e32 v38, v26, v27
	s_waitcnt vmcnt(0)
; __device__ __forceinline__ float sigmoidf_(float x) { return __builtin_amdgcn_rcpf(1.0f + __expf(-x)); }
; template <int N> __device__ __forceinline__ float dpp_ror(float v) { return __builtin_bit_cast(float, __builtin_amdgcn_update_dpp(0, __builtin_bit_cast(int, v), 0x120 + N, 0xf, 0xf, false)); }
;     __device__ __forceinline__ void operator()(Acc& acc, const Unit& u, int wr, int wc, int fr, int fq) const {
;     ...
;                 const float g0 = cw[cg_], g1 = cw[NUP + cg_], g2 = cw[2 * NUP + cg_], gb = cb[cg_];
;                 const float v0 = cw[cv_], v1 = cw[NUP + cv_], v2 = cw[2 * NUP + cv_], vb = cb[cv_];
;                 float pg1 = 0.f, pg2 = 0.f, pv1 = 0.f, pv2 = 0.f;
; #pragma unroll
;                 for (int q = 0; q < 8; ++q) {
;                     float cgv = acc[q >> 2][0][q & 3][n][i], cvv = acc[q >> 2][1][q & 3][n][i];
;                     asm volatile("" : "+v"(cgv), "+v"(cvv) : "v"(chain));
;                     const float tg1 = dpp_ror<1>(cgv), tg2 = dpp_ror<2>(cgv), tv1 = dpp_ror<1>(cvv), tv2 = dpp_ror<2>(cvv);
;                     const float sg1 = fr >= 1 ? tg1 : pg1, sg2 = fr >= 2 ? tg2 : pg2, sv1 = fr >= 1 ? tv1 : pv1, sv2 = fr >= 2 ? tv2 : pv2;
;                     const float gg = gb + g0 * sg2 + g1 * sg1 + g2 * cgv;
;                     const float vv = vb + v0 * sv2 + v1 * sv1 + v2 * cvv;
;                     chain = gg * sigmoidf_(gg) * vv; acc[q >> 2][0][q & 3][n][i] = chain;
;                     pg1 = tg1; pg2 = tg2; pv1 = tv1; pv2 = tv2;
;                 }
	v_mov_b32_e32 v33, v240
	v_mov_b32_e32 v27, v241
	v_mov_b32_e32 v26, v242
	v_mov_b32_e32 v35, v243
	v_mov_b32_e32 v34, v244
	v_mov_b32_e32 v32, v245
	v_mov_b32_e32 v41, v246
	v_mov_b32_e32 v40, v247
	global_load_dword v232, v[6:7], off offset:28
	global_load_dword v233, v[8:9], off offset:2076
	global_load_dword v234, v[10:11], off offset:28
	global_load_dword v235, v[16:17], off offset:28
	global_load_dword v236, v[18:19], off offset:3100
	global_load_dword v237, v[22:23], off offset:1052
	global_load_dword v238, v[24:25], off offset:3100
	global_load_dword v239, v[20:21], off offset:3100
	v_mov_b32_dpp v67, v122 row_ror:1 row_mask:0xf bank_mask:0xf
	v_mov_b32_dpp v83, v122 row_ror:2 row_mask:0xf bank_mask:0xf
	v_cndmask_b32_e64 v123, v67, 0, s[38:39]
	v_cndmask_b32_e64 v36, 0, v83, s[40:41]
	v_mov_b32_dpp v84, v124 row_ror:1 row_mask:0xf bank_mask:0xf
	v_cndmask_b32_e64 v125, v84, 0, s[38:39]
	v_mov_b32_dpp v85, v124 row_ror:2 row_mask:0xf bank_mask:0xf
	v_cndmask_b32_e64 v39, 0, v85, s[40:41]
	s_nop 0
	v_fma_f32 v80, v33, v36, v35
	v_pk_mul_f32 v[36:37], v[26:27], v[122:123]
	s_nop 0
	v_fma_f32 v39, v32, v39, v34
	v_add_f32_e32 v37, v37, v80
	v_add_f32_e32 v100, v36, v37
	v_mul_f32_e32 v36, 0xbfb8aa3b, v100
	v_exp_f32_e32 v101, v36
	v_mov_b32_e32 v37, v26
	s_nop 0
	v_pk_mul_f32 v[80:81], v[40:41], v[124:125]
	v_mov_b32_e32 v36, v40
	v_add_f32_e32 v26, 1.0, v101
	v_rcp_f32_e32 v40, v26
	v_add_f32_e32 v39, v81, v39
	v_add_f32_e32 v39, v80, v39
	v_mov_b32_e32 v26, v41
	v_mul_f32_e32 v40, v100, v40
	v_mul_f32_e32 v39, v39, v40
	v_mov_b32_dpp v87, v113 row_ror:2 row_mask:0xf bank_mask:0xf
	v_mov_b32_dpp v97, v112 row_ror:2 row_mask:0xf bank_mask:0xf
	v_mov_b32_dpp v86, v113 row_ror:1 row_mask:0xf bank_mask:0xf
	v_mov_b32_dpp v96, v112 row_ror:1 row_mask:0xf bank_mask:0xf
	v_cndmask_b32_e64 v81, v83, v87, s[40:41]
	v_cndmask_b32_e64 v80, v85, v97, s[40:41]
	v_cndmask_b32_e64 v41, v86, v67, s[38:39]
	v_cndmask_b32_e64 v40, v96, v84, s[38:39]
	v_pk_fma_f32 v[80:81], v[32:33], v[80:81], v[34:35]
	v_pk_fma_f32 v[40:41], v[26:27], v[40:41], v[80:81]
	s_nop 0
	v_pk_fma_f32 v[40:41], v[36:37], v[112:113], v[40:41]
	s_nop 0
	v_mul_f32_e32 v67, 0xbfb8aa3b, v41
	v_exp_f32_e32 v67, v67
	s_nop 0
	v_add_f32_e32 v67, 1.0, v67
	v_rcp_f32_e32 v67, v67
	s_nop 0
	v_mul_f32_e32 v41, v41, v67
	v_mul_f32_e32 v40, v40, v41
	v_mov_b32_dpp v100, v95 row_ror:2 row_mask:0xf bank_mask:0xf
	v_mov_b32_dpp v102, v94 row_ror:2 row_mask:0xf bank_mask:0xf
	v_mov_b32_dpp v83, v95 row_ror:1 row_mask:0xf bank_mask:0xf
	v_mov_b32_dpp v101, v94 row_ror:1 row_mask:0xf bank_mask:0xf
	v_cndmask_b32_e64 v85, v87, v100, s[40:41]
	v_cndmask_b32_e64 v84, v97, v102, s[40:41]
	v_cndmask_b32_e64 v81, v83, v86, s[38:39]
	v_cndmask_b32_e64 v80, v101, v96, s[38:39]
	v_pk_fma_f32 v[84:85], v[32:33], v[84:85], v[34:35]
	v_pk_fma_f32 v[80:81], v[26:27], v[80:81], v[84:85]
	v_pk_fma_f32 v[80:81], v[36:37], v[94:95], v[80:81]
	v_mul_f32_e32 v41, 0xbfb8aa3b, v81
	v_exp_f32_e32 v41, v41
	s_nop 0
	v_add_f32_e32 v41, 1.0, v41
	v_rcp_f32_e32 v41, v41
	s_nop 0
	v_mul_f32_e32 v41, v81, v41
	v_mul_f32_e32 v41, v80, v41
	v_mov_b32_dpp v87, v79 row_ror:2 row_mask:0xf bank_mask:0xf
	v_mov_b32_dpp v95, v78 row_ror:2 row_mask:0xf bank_mask:0xf
	v_mov_b32_dpp v86, v79 row_ror:1 row_mask:0xf bank_mask:0xf
	v_mov_b32_dpp v94, v78 row_ror:1 row_mask:0xf bank_mask:0xf
	v_cndmask_b32_e64 v85, v100, v87, s[40:41]
	v_cndmask_b32_e64 v84, v102, v95, s[40:41]
	v_cndmask_b32_e64 v81, v86, v83, s[38:39]
	v_cndmask_b32_e64 v80, v94, v101, s[38:39]
	v_pk_fma_f32 v[84:85], v[32:33], v[84:85], v[34:35]
	v_pk_fma_f32 v[80:81], v[26:27], v[80:81], v[84:85]
	v_pk_fma_f32 v[78:79], v[36:37], v[78:79], v[80:81]
	v_mul_f32_e32 v67, 0xbfb8aa3b, v79
	v_exp_f32_e32 v67, v67
	s_nop 0
	v_add_f32_e32 v67, 1.0, v67
	v_rcp_f32_e32 v67, v67
	s_nop 0
	v_mul_f32_e32 v67, v79, v67
	v_mul_f32_e32 v67, v78, v67
	v_mov_b32_dpp v84, v65 row_ror:2 row_mask:0xf bank_mask:0xf
	v_mov_b32_dpp v96, v64 row_ror:2 row_mask:0xf bank_mask:0xf
	v_mov_b32_dpp v83, v65 row_ror:1 row_mask:0xf bank_mask:0xf
	v_mov_b32_dpp v85, v64 row_ror:1 row_mask:0xf bank_mask:0xf
	v_cndmask_b32_e64 v81, v87, v84, s[40:41]
	v_cndmask_b32_e64 v80, v95, v96, s[40:41]
	v_cndmask_b32_e64 v79, v83, v86, s[38:39]
	v_cndmask_b32_e64 v78, v85, v94, s[38:39]
	v_pk_fma_f32 v[80:81], v[32:33], v[80:81], v[34:35]
	v_pk_fma_f32 v[78:79], v[26:27], v[78:79], v[80:81]
	v_pk_fma_f32 v[64:65], v[36:37], v[64:65], v[78:79]
	v_mul_f32_e32 v78, 0xbfb8aa3b, v65
	v_exp_f32_e32 v78, v78
	s_nop 0
	v_add_f32_e32 v78, 1.0, v78
	v_rcp_f32_e32 v78, v78
	s_nop 0
	v_mul_f32_e32 v65, v65, v78
	v_mul_f32_e32 v64, v64, v65
	v_mov_b32_dpp v87, v47 row_ror:2 row_mask:0xf bank_mask:0xf
	v_mov_b32_dpp v95, v46 row_ror:2 row_mask:0xf bank_mask:0xf
	v_mov_b32_dpp v86, v47 row_ror:1 row_mask:0xf bank_mask:0xf
	v_mov_b32_dpp v94, v46 row_ror:1 row_mask:0xf bank_mask:0xf
	v_cndmask_b32_e64 v81, v84, v87, s[40:41]
	v_cndmask_b32_e64 v80, v96, v95, s[40:41]
	v_cndmask_b32_e64 v79, v86, v83, s[38:39]
	v_cndmask_b32_e64 v78, v94, v85, s[38:39]
	v_pk_fma_f32 v[80:81], v[32:33], v[80:81], v[34:35]
	v_pk_fma_f32 v[78:79], v[26:27], v[78:79], v[80:81]
	v_pk_fma_f32 v[46:47], v[36:37], v[46:47], v[78:79]
	v_mul_f32_e32 v65, 0xbfb8aa3b, v47
	v_exp_f32_e32 v65, v65
	s_nop 0
	v_add_f32_e32 v65, 1.0, v65
	v_rcp_f32_e32 v65, v65
	s_nop 0
	v_mul_f32_e32 v47, v47, v65
	v_mul_f32_e32 v46, v46, v47
	v_mov_b32_dpp v84, v31 row_ror:2 row_mask:0xf bank_mask:0xf
	v_mov_b32_dpp v96, v30 row_ror:2 row_mask:0xf bank_mask:0xf
	v_mov_b32_dpp v83, v31 row_ror:1 row_mask:0xf bank_mask:0xf
	v_mov_b32_dpp v85, v30 row_ror:1 row_mask:0xf bank_mask:0xf
	v_cndmask_b32_e64 v81, v87, v84, s[40:41]
	v_cndmask_b32_e64 v80, v95, v96, s[40:41]
	v_cndmask_b32_e64 v79, v83, v86, s[38:39]
	v_cndmask_b32_e64 v78, v85, v94, s[38:39]
	v_pk_fma_f32 v[80:81], v[32:33], v[80:81], v[34:35]
	v_pk_fma_f32 v[78:79], v[26:27], v[78:79], v[80:81]
	v_pk_fma_f32 v[30:31], v[36:37], v[30:31], v[78:79]
	v_mul_f32_e32 v47, 0xbfb8aa3b, v31
	v_exp_f32_e32 v47, v47
	s_nop 0
	v_add_f32_e32 v47, 1.0, v47
	v_rcp_f32_e32 v47, v47
	s_nop 0
	v_mul_f32_e32 v31, v31, v47
	v_mul_f32_e32 v30, v30, v31
	v_mov_b32_dpp v80, v15 row_ror:2 row_mask:0xf bank_mask:0xf
	v_mov_b32_dpp v86, v14 row_ror:2 row_mask:0xf bank_mask:0xf
	v_mov_b32_dpp v65, v15 row_ror:1 row_mask:0xf bank_mask:0xf
	v_mov_b32_dpp v78, v14 row_ror:1 row_mask:0xf bank_mask:0xf
	v_cndmask_b32_e64 v81, v84, v80, s[40:41]
	v_cndmask_b32_e64 v80, v96, v86, s[40:41]
	v_cndmask_b32_e64 v79, v65, v83, s[38:39]
	v_cndmask_b32_e64 v78, v78, v85, s[38:39]
	v_pk_fma_f32 v[32:33], v[32:33], v[80:81], v[34:35]
	s_nop 0
	v_pk_fma_f32 v[26:27], v[26:27], v[78:79], v[32:33]
	s_nop 0
	v_pk_fma_f32 v[14:15], v[36:37], v[14:15], v[26:27]
	s_nop 0
	v_mul_f32_e32 v26, 0xbfb8aa3b, v15
	v_exp_f32_e32 v26, v26
	s_nop 0
	v_add_f32_e32 v26, 1.0, v26
	v_rcp_f32_e32 v26, v26
	s_nop 0
	v_mul_f32_e32 v15, v15, v26
	v_mul_f32_e32 v26, v14, v15
	s_waitcnt vmcnt(0)
; __device__ __forceinline__ unsigned pk2(float lo, float hi) { const f32x2_t v = {lo, hi}; const bf16x2_t b = __builtin_convertvector(v, bf16x2_t); return __builtin_bit_cast(unsigned, b); }
; __device__ __forceinline__ float sigmoidf_(float x) { return __builtin_amdgcn_rcpf(1.0f + __expf(-x)); }
; template <int N> __device__ __forceinline__ float dpp_ror(float v) { return __builtin_bit_cast(float, __builtin_amdgcn_update_dpp(0, __builtin_bit_cast(int, v), 0x120 + N, 0xf, 0xf, false)); }
;     __device__ __forceinline__ void operator()(Acc& acc, const Unit& u, int wr, int wc, int fr, int fq) const {
;     ...
;                 for (int q = 0; q < 8; ++q) {
;                     float cgv = acc[q >> 2][0][q & 3][n][i], cvv = acc[q >> 2][1][q & 3][n][i];
;                     asm volatile("" : "+v"(cgv), "+v"(cvv) : "v"(chain));
;                     const float tg1 = dpp_ror<1>(cgv), tg2 = dpp_ror<2>(cgv), tv1 = dpp_ror<1>(cvv), tv2 = dpp_ror<2>(cvv);
;                     const float sg1 = fr >= 1 ? tg1 : pg1, sg2 = fr >= 2 ? tg2 : pg2, sv1 = fr >= 1 ? tv1 : pv1, sv2 = fr >= 2 ? tv2 : pv2;
;                     const float gg = gb + g0 * sg2 + g1 * sg1 + g2 * cgv;
;                     const float vv = vb + v0 * sv2 + v1 * sv1 + v2 * cvv;
;                     chain = gg * sigmoidf_(gg) * vv; acc[q >> 2][0][q & 3][n][i] = chain;
;                     pg1 = tg1; pg2 = tg2; pv1 = tv1; pv2 = tv2;
;                 }
;     ...
;         for (int q = 0; q < 8; ++q) {
;             const int t = tbase + 16 * q;
;             if ((16 * q + fr >= 2) && (t < SEQ)) {
;                 const f32x4 a0 = acc[q >> 2][0][q & 3][0], a1 = acc[q >> 2][0][q & 3][1];
;                 u32x4 w; w.x = pk2(a0[0], a0[1]); w.y = pk2(a0[2], a0[3]); w.z = pk2(a1[0], a1[1]); w.w = pk2(a1[2], a1[3]);
;                 *(u32x4*)(act + (size_t)(b * SEQ + t) * DFF + ch0) = w;
;             }
	v_mov_b32_e32 v15, v232
	s_nop 0
	v_mov_b32_e32 v7, v233
	v_mov_b32_e32 v6, v234
	s_nop 0
	v_mov_b32_e32 v9, v235
	v_mov_b32_e32 v14, v236
	s_nop 0
	v_mov_b32_e32 v17, v237
	v_mov_b32_e32 v16, v238
	v_mov_b32_e32 v8, v239
	v_mov_b32_dpp v19, v120 row_ror:1 row_mask:0xf bank_mask:0xf
	v_mov_b32_dpp v22, v120 row_ror:2 row_mask:0xf bank_mask:0xf
	v_cndmask_b32_e64 v121, v19, 0, s[38:39]
	v_cndmask_b32_e64 v10, 0, v22, s[40:41]
	v_mov_b32_dpp v20, v110 row_ror:1 row_mask:0xf bank_mask:0xf
	v_mov_b32_dpp v24, v110 row_ror:2 row_mask:0xf bank_mask:0xf
	v_cndmask_b32_e64 v111, v20, 0, s[38:39]
	v_cndmask_b32_e64 v18, 0, v24, s[40:41]
	v_mov_b32_e32 v35, v3
	v_mov_b32_e32 v36, v3
	s_nop 0
	v_fma_f32 v21, v15, v10, v9
	v_pk_mul_f32 v[10:11], v[6:7], v[120:121]
	s_nop 0
	v_fma_f32 v18, v14, v18, v8
	v_add_f32_e32 v11, v11, v21
	v_add_f32_e32 v21, v10, v11
	v_pk_mul_f32 v[10:11], v[16:17], v[110:111]
	s_nop 0
	v_add_f32_e32 v11, v11, v18
	v_add_f32_e32 v10, v10, v11
	v_mul_f32_e32 v11, 0xbfb8aa3b, v21
	v_exp_f32_e32 v11, v11
	s_nop 0
	v_add_f32_e32 v11, 1.0, v11
	v_rcp_f32_e32 v11, v11
	s_nop 0
	v_mul_f32_e32 v11, v21, v11
	v_mul_f32_e32 v18, v10, v11
	v_mov_b32_e32 v11, v6
	v_mov_b32_e32 v6, v17
	v_mov_b32_dpp v27, v109 row_ror:2 row_mask:0xf bank_mask:0xf
	v_mov_b32_dpp v32, v108 row_ror:2 row_mask:0xf bank_mask:0xf
	v_mov_b32_dpp v25, v109 row_ror:1 row_mask:0xf bank_mask:0xf
	v_mov_b32_dpp v31, v108 row_ror:1 row_mask:0xf bank_mask:0xf
	v_cndmask_b32_e64 v23, v22, v27, s[40:41]
	v_cndmask_b32_e64 v22, v24, v32, s[40:41]
	v_cndmask_b32_e64 v21, v25, v19, s[38:39]
	v_cndmask_b32_e64 v20, v31, v20, s[38:39]
	v_pk_fma_f32 v[22:23], v[14:15], v[22:23], v[8:9]
	v_mov_b32_e32 v10, v16
	v_pk_fma_f32 v[16:17], v[6:7], v[20:21], v[22:23]
	v_pk_fma_f32 v[16:17], v[10:11], v[108:109], v[16:17]
	s_nop 0
	v_mul_f32_e32 v19, 0xbfb8aa3b, v17
	v_exp_f32_e32 v19, v19
	s_nop 0
	v_add_f32_e32 v19, 1.0, v19
	v_rcp_f32_e32 v19, v19
	s_nop 0
	v_mul_f32_e32 v17, v17, v19
	v_mul_f32_e32 v16, v16, v17
	v_mov_b32_dpp v24, v93 row_ror:2 row_mask:0xf bank_mask:0xf
	v_mov_b32_dpp v34, v92 row_ror:2 row_mask:0xf bank_mask:0xf
	v_mov_b32_dpp v19, v93 row_ror:1 row_mask:0xf bank_mask:0xf
	v_mov_b32_dpp v33, v92 row_ror:1 row_mask:0xf bank_mask:0xf
	v_cndmask_b32_e64 v23, v27, v24, s[40:41]
	v_cndmask_b32_e64 v22, v32, v34, s[40:41]
	v_cndmask_b32_e64 v21, v19, v25, s[38:39]
	v_cndmask_b32_e64 v20, v33, v31, s[38:39]
	v_pk_fma_f32 v[22:23], v[14:15], v[22:23], v[8:9]
	v_pk_fma_f32 v[20:21], v[6:7], v[20:21], v[22:23]
	v_pk_fma_f32 v[20:21], v[10:11], v[92:93], v[20:21]
	v_mul_f32_e32 v17, 0xbfb8aa3b, v21
	v_exp_f32_e32 v17, v17
	s_nop 0
	v_add_f32_e32 v17, 1.0, v17
	v_rcp_f32_e32 v17, v17
	s_nop 0
	v_mul_f32_e32 v17, v21, v17
	v_mul_f32_e32 v17, v20, v17
	v_mov_b32_dpp v27, v77 row_ror:2 row_mask:0xf bank_mask:0xf
	v_mov_b32_dpp v32, v76 row_ror:2 row_mask:0xf bank_mask:0xf
	v_mov_b32_dpp v25, v77 row_ror:1 row_mask:0xf bank_mask:0xf
	v_mov_b32_dpp v31, v76 row_ror:1 row_mask:0xf bank_mask:0xf
	v_cndmask_b32_e64 v23, v24, v27, s[40:41]
	v_cndmask_b32_e64 v22, v34, v32, s[40:41]
	v_cndmask_b32_e64 v21, v25, v19, s[38:39]
	v_cndmask_b32_e64 v20, v31, v33, s[38:39]
	v_pk_fma_f32 v[22:23], v[14:15], v[22:23], v[8:9]
	v_pk_fma_f32 v[20:21], v[6:7], v[20:21], v[22:23]
	v_pk_fma_f32 v[20:21], v[10:11], v[76:77], v[20:21]
	v_mul_f32_e32 v19, 0xbfb8aa3b, v21
	v_exp_f32_e32 v19, v19
	s_nop 0
	v_add_f32_e32 v19, 1.0, v19
	v_rcp_f32_e32 v19, v19
	s_nop 0
	v_mul_f32_e32 v19, v21, v19
	v_mul_f32_e32 v19, v20, v19
	v_mov_b32_dpp v33, v61 row_ror:2 row_mask:0xf bank_mask:0xf
	v_mov_b32_dpp v35, v60 row_ror:2 row_mask:0xf bank_mask:0xf
	v_mov_b32_dpp v24, v61 row_ror:1 row_mask:0xf bank_mask:0xf
	v_mov_b32_dpp v34, v60 row_ror:1 row_mask:0xf bank_mask:0xf
	v_cndmask_b32_e64 v23, v27, v33, s[40:41]
	v_cndmask_b32_e64 v22, v32, v35, s[40:41]
	v_cndmask_b32_e64 v21, v24, v25, s[38:39]
	v_cndmask_b32_e64 v20, v34, v31, s[38:39]
	v_pk_fma_f32 v[22:23], v[14:15], v[22:23], v[8:9]
	v_pk_fma_f32 v[20:21], v[6:7], v[20:21], v[22:23]
	v_pk_fma_f32 v[20:21], v[10:11], v[60:61], v[20:21]
	v_mul_f32_e32 v22, 0xbfb8aa3b, v21
	v_exp_f32_e32 v22, v22
	s_nop 0
	v_add_f32_e32 v22, 1.0, v22
	v_rcp_f32_e32 v22, v22
	s_nop 0
	v_mul_f32_e32 v21, v21, v22
	v_mul_f32_e32 v20, v20, v21
	v_mov_b32_dpp v27, v45 row_ror:1 row_mask:0xf bank_mask:0xf
	v_mov_b32_dpp v31, v45 row_ror:2 row_mask:0xf bank_mask:0xf
	v_mov_b32_dpp v36, v44 row_ror:2 row_mask:0xf bank_mask:0xf
	v_mov_b32_dpp v32, v44 row_ror:1 row_mask:0xf bank_mask:0xf
	v_cndmask_b32_e64 v23, v27, v24, s[38:39]
	v_cndmask_b32_e64 v25, v33, v31, s[40:41]
	v_cndmask_b32_e64 v24, v35, v36, s[40:41]
	v_cndmask_b32_e64 v22, v32, v34, s[38:39]
	v_pk_fma_f32 v[24:25], v[14:15], v[24:25], v[8:9]
	s_nop 0
	v_pk_fma_f32 v[22:23], v[6:7], v[22:23], v[24:25]
	v_pk_fma_f32 v[22:23], v[10:11], v[44:45], v[22:23]
	s_nop 0
	v_mul_f32_e32 v21, 0xbfb8aa3b, v23
	v_exp_f32_e32 v21, v21
	s_nop 0
	v_add_f32_e32 v21, 1.0, v21
	v_rcp_f32_e32 v21, v21
	s_nop 0
	v_mul_f32_e32 v21, v23, v21
	v_mul_f32_e32 v24, v22, v21
	v_mov_b32_dpp v22, v29 row_ror:2 row_mask:0xf bank_mask:0xf
	v_mov_b32_dpp v25, v28 row_ror:2 row_mask:0xf bank_mask:0xf
	v_mov_b32_dpp v21, v29 row_ror:1 row_mask:0xf bank_mask:0xf
	v_mov_b32_dpp v23, v28 row_ror:1 row_mask:0xf bank_mask:0xf
	v_cndmask_b32_e64 v35, v31, v22, s[40:41]
	v_cndmask_b32_e64 v34, v36, v25, s[40:41]
	v_cndmask_b32_e64 v33, v21, v27, s[38:39]
	v_cndmask_b32_e64 v32, v23, v32, s[38:39]
	v_pk_fma_f32 v[34:35], v[14:15], v[34:35], v[8:9]
	v_pk_fma_f32 v[32:33], v[6:7], v[32:33], v[34:35]
	s_nop 0
	v_pk_fma_f32 v[28:29], v[10:11], v[28:29], v[32:33]
	v_mul_f32_e32 v27, 0xbfb8aa3b, v29
	v_exp_f32_e32 v27, v27
	s_nop 0
	v_add_f32_e32 v27, 1.0, v27
	v_rcp_f32_e32 v27, v27
	s_nop 0
	v_mul_f32_e32 v27, v29, v27
	v_mul_f32_e32 v27, v28, v27
	s_nop 0
	v_mov_b32_dpp v28, v13 row_ror:1 row_mask:0xf bank_mask:0xf
	v_mov_b32_dpp v29, v13 row_ror:2 row_mask:0xf bank_mask:0xf
	v_mov_b32_dpp v31, v12 row_ror:1 row_mask:0xf bank_mask:0xf
	v_mov_b32_dpp v32, v12 row_ror:2 row_mask:0xf bank_mask:0xf
	v_cmp_gt_i32_e32 vcc, s97, v198
	s_and_b64 s[44:45], s[40:41], vcc
	s_and_saveexec_b64 s[34:35], s[44:45]
	s_cbranch_execz .LBB0_45
	v_cvt_pk_bf16_f32 v37, v39, v18
	v_add_u32_e32 v18, s20, v198
	v_mov_b64_e32 v[44:45], s[8:9]
	s_movk_i32 s21, 0x1600
	v_mad_i64_i32 v[44:45], s[44:45], v18, s21, v[44:45]
	v_cvt_pk_bf16_f32 v34, v184, v137
	v_cvt_pk_bf16_f32 v35, v99, v63
	v_cvt_pk_bf16_f32 v36, v56, v43
	v_lshl_add_u64 v[44:45], v[4:5], 1, v[44:45]
	flat_store_dwordx4 v[44:45], v[34:37]
